# GEMM K-loops: the s_setprio 0 / s_setprio 1 pair in the middle of each 32-MFMA block removed (on top of the early barrier)
# baseline (speedup 1.0000x reference)
; #define PG8_STAGE(bufoff, gbase, voff) do { _Pragma("unroll") for (int _i = 0; _i < 2; ++_i) \
;         __builtin_amdgcn_global_load_lds((const unsigned*)((const char*)(gbase) + (voff)[_i]), (PG8_LAS unsigned*)(lds + (bufoff) + ldsw + _i * 8192), 16, 0, 0); } while (0)
; #define PG8_LDA(dst, b, h) do { _Pragma("unroll") for (int m = 0; m < 4; ++m) _Pragma("unroll") for (int k = 0; k < 2; ++k) dst[m][k] = *(const PG8_LAS bf16x8*)(lds + PG8_SA(b, h) + aoff + m * 2048 + k * 1024); } while (0)
; #define PG8_LDB(dst, b, h) do { _Pragma("unroll") for (int n = 0; n < 2; ++n) _Pragma("unroll") for (int k = 0; k < 2; ++k) dst[n][k] = *(const PG8_LAS bf16x8*)(lds + PG8_SB(b, h) + boff + n * 2048 + k * 1024); } while (0)
; #define PG8_MMA(ai, bj, At, Bt) do { __builtin_amdgcn_s_setprio(1); _Pragma("unroll") for (int m = 0; m < 4; ++m) _Pragma("unroll") for (int n = 0; n < 2; ++n) _Pragma("unroll") for (int k = 0; k < 2; ++k) \
;         acc[ai][bj][m][n] = __builtin_amdgcn_mfma_f32_16x16x32_bf16(Bt[n][k], At[m][k], acc[ai][bj][m][n], 0, 0, 0); __builtin_amdgcn_s_setprio(0); } while (0)
; #define PG8_WAIT_V(n) asm volatile("s_waitcnt vmcnt(" #n ")" ::: "memory")
; #define PG8_WAIT_L(n) asm volatile("s_waitcnt lgkmcnt(" #n ")" ::: "memory")
; #define PG8_BAR __builtin_amdgcn_s_barrier()
; #define PG8_SCHED __builtin_amdgcn_sched_barrier(0)
; template <class Epi, class Sched, bool ALIGN_EPI = false, bool SP2 = false>
; __device__ __forceinline__ void gemm_phase(PG8_LAS unsigned char* lds, const Gemm g, const Sched& S, const Epi& E) {
;     ...
;             const bool last = (t == nt - 2);
;             const char* a1 = cA + (size_t)(t + 1) * kstep;
;             const char* a2 = last ? nA : cA + (size_t)(t + 2) * kstep; const char* b2 = last ? nB : cB + (size_t)(t + 2) * kstep;
;             const char* a3 = a2 + kstep; const char* b3 = b2 + kstep;
;             if (last && has_next) S.a_ready(nxt);
;             if constexpr (SP2) {
;             PG8_LDB(B0, 0, 0); PG8_LDB(B1, 0, 1); PG8_SCHED; PG8_LDA(At, 0, 0); PG8_STAGE(PG8_SA(1, 1), a1 + hstep, voffA);
;             PG8_WAIT_V(8); PG8_WAIT_L(0); PG8_BAR; PG8_MMA(0, 0, At, B0); PG8_MMA(0, 1, At, B1); PG8_BAR; PG8_SCHED;
;             PG8_LDA(At, 0, 1); PG8_STAGE(PG8_SB(0, 0), b2, voffB); PG8_STAGE(PG8_SB(0, 1), b2 + hstep, voffB); PG8_STAGE(PG8_SA(0, 0), a2, voffA);
.LBB0_121:
	s_add_u32 s46, s44, 0xfffc0080
	s_addc_u32 s47, s45, -1
	s_add_i32 s64, 0, 0x10000
	s_cmp_eq_u32 s63, 12
	s_cselect_b32 s49, s41, s47
	s_cselect_b32 s48, s40, s46
	v_add_u32_e32 v146, s64, v149
	s_cselect_b32 s47, s37, s62
	s_cselect_b32 s46, s39, s61
	s_add_i32 s67, 0, 0x14000
	ds_read_b128 v[152:155], v146
	ds_read_b128 v[156:159], v146 offset:1024
	ds_read_b128 v[160:163], v146 offset:2048
	ds_read_b128 v[174:177], v146 offset:3072
	v_add_u32_e32 v146, s67, v149
	ds_read_b128 v[178:181], v146
	ds_read_b128 v[182:185], v146 offset:1024
	ds_read_b128 v[186:189], v146 offset:2048
	ds_read_b128 v[190:193], v146 offset:3072
	v_lshl_add_u64 v[146:147], s[44:45], 0, v[142:143]
	s_add_i32 m0, s52, 0xc000
	ds_read_b128 v[194:197], v151
	ds_read_b128 v[198:201], v151 offset:1024
	ds_read_b128 v[202:205], v151 offset:2048
	ds_read_b128 v[206:209], v151 offset:3072
	ds_read_b128 v[210:213], v151 offset:4096
	ds_read_b128 v[214:217], v151 offset:5120
	ds_read_b128 v[218:221], v151 offset:6144
	ds_read_b128 v[222:225], v151 offset:7168
	global_load_lds_dwordx4 v[146:147], off
	v_lshl_add_u64 v[146:147], s[44:45], 0, v[144:145]
	s_add_i32 m0, s52, 0xe000
	s_nop 0
	global_load_lds_dwordx4 v[146:147], off
	s_waitcnt vmcnt(8)
	s_waitcnt lgkmcnt(0)
	s_barrier
	s_setprio 1
	s_waitcnt lgkmcnt(0)
	v_mfma_f32_16x16x32_bf16 v[126:129], v[152:155], v[194:197], v[126:129]
	v_mfma_f32_16x16x32_bf16 v[122:125], v[160:163], v[194:197], v[122:125]
	v_mfma_f32_16x16x32_bf16 v[118:121], v[152:155], v[202:205], v[118:121]
	v_mfma_f32_16x16x32_bf16 v[110:113], v[160:163], v[202:205], v[110:113]
	v_mfma_f32_16x16x32_bf16 v[102:105], v[152:155], v[210:213], v[102:105]
	v_mfma_f32_16x16x32_bf16 v[94:97], v[160:163], v[210:213], v[94:97]
	v_mfma_f32_16x16x32_bf16 v[86:89], v[152:155], v[218:221], v[86:89]
	v_mfma_f32_16x16x32_bf16 v[78:81], v[160:163], v[218:221], v[78:81]
	v_mfma_f32_16x16x32_bf16 v[126:129], v[156:159], v[198:201], v[126:129]
	v_mfma_f32_16x16x32_bf16 v[122:125], v[174:177], v[198:201], v[122:125]
	v_mfma_f32_16x16x32_bf16 v[118:121], v[156:159], v[206:209], v[118:121]
	v_mfma_f32_16x16x32_bf16 v[110:113], v[174:177], v[206:209], v[110:113]
	v_mfma_f32_16x16x32_bf16 v[102:105], v[156:159], v[214:217], v[102:105]
	v_mfma_f32_16x16x32_bf16 v[94:97], v[174:177], v[214:217], v[94:97]
	v_mfma_f32_16x16x32_bf16 v[86:89], v[156:159], v[222:225], v[86:89]
	v_mfma_f32_16x16x32_bf16 v[78:81], v[174:177], v[222:225], v[78:81]
	v_mfma_f32_16x16x32_bf16 v[114:117], v[178:181], v[194:197], v[114:117]
	v_mfma_f32_16x16x32_bf16 v[106:109], v[186:189], v[194:197], v[106:109]
	v_mfma_f32_16x16x32_bf16 v[98:101], v[178:181], v[202:205], v[98:101]
	v_mfma_f32_16x16x32_bf16 v[90:93], v[186:189], v[202:205], v[90:93]
	v_mfma_f32_16x16x32_bf16 v[82:85], v[178:181], v[210:213], v[82:85]
	v_mfma_f32_16x16x32_bf16 v[74:77], v[186:189], v[210:213], v[74:77]
	v_mfma_f32_16x16x32_bf16 v[70:73], v[178:181], v[218:221], v[70:73]
	v_mfma_f32_16x16x32_bf16 v[66:69], v[186:189], v[218:221], v[66:69]
	v_mfma_f32_16x16x32_bf16 v[114:117], v[182:185], v[198:201], v[114:117]
	v_mfma_f32_16x16x32_bf16 v[106:109], v[190:193], v[198:201], v[106:109]
	v_mfma_f32_16x16x32_bf16 v[98:101], v[182:185], v[206:209], v[98:101]
	v_mfma_f32_16x16x32_bf16 v[90:93], v[190:193], v[206:209], v[90:93]
	v_mfma_f32_16x16x32_bf16 v[82:85], v[182:185], v[214:217], v[82:85]
	v_mfma_f32_16x16x32_bf16 v[74:77], v[190:193], v[214:217], v[74:77]
	v_mfma_f32_16x16x32_bf16 v[70:73], v[182:185], v[222:225], v[70:73]
	s_barrier
	v_mfma_f32_16x16x32_bf16 v[66:69], v[190:193], v[222:225], v[66:69]
	s_setprio 0
	s_add_i32 s64, s64, s34
	v_lshl_add_u64 v[146:147], s[46:47], 0, v[130:131]
	s_mov_b32 m0, s64
	ds_read_b128 v[194:197], v151 offset:16384
	ds_read_b128 v[198:201], v151 offset:17408
	ds_read_b128 v[202:205], v151 offset:18432
	ds_read_b128 v[206:209], v151 offset:19456
	ds_read_b128 v[210:213], v151 offset:20480
	ds_read_b128 v[214:217], v151 offset:21504
	ds_read_b128 v[218:221], v151 offset:22528
	ds_read_b128 v[222:225], v151 offset:23552
	global_load_lds_dwordx4 v[146:147], off
	s_add_i32 m0, s64, 0x2000
	s_add_u32 s64, s46, 0x40000
	v_lshl_add_u64 v[226:227], s[46:47], 0, v[136:137]
	s_addc_u32 s65, s47, 0
	s_add_i32 s67, s67, s34
	global_load_lds_dwordx4 v[226:227], off
	v_lshl_add_u64 v[228:229], s[64:65], 0, v[130:131]
	s_mov_b32 m0, s67
	v_lshl_add_u64 v[230:231], s[48:49], 0, v[138:139]
	global_load_lds_dwordx4 v[228:229], off
	v_lshl_add_u64 v[228:229], s[64:65], 0, v[136:137]
	s_add_i32 m0, s67, 0x2000
	s_nop 0
	global_load_lds_dwordx4 v[228:229], off
	v_lshl_add_u64 v[228:229], s[48:49], 0, v[140:141]
	s_mov_b32 m0, s52
	s_nop 0
	global_load_lds_dwordx4 v[228:229], off
	s_mov_b32 m0, s53
	s_nop 0
	global_load_lds_dwordx4 v[230:231], off
	s_waitcnt vmcnt(8)
	s_waitcnt lgkmcnt(0)
	s_barrier
; #define PG8_STAGE(bufoff, gbase, voff) do { _Pragma("unroll") for (int _i = 0; _i < 2; ++_i) \
;         __builtin_amdgcn_global_load_lds((const unsigned*)((const char*)(gbase) + (voff)[_i]), (PG8_LAS unsigned*)(lds + (bufoff) + ldsw + _i * 8192), 16, 0, 0); } while (0)
; #define PG8_LDA(dst, b, h) do { _Pragma("unroll") for (int m = 0; m < 4; ++m) _Pragma("unroll") for (int k = 0; k < 2; ++k) dst[m][k] = *(const PG8_LAS bf16x8*)(lds + PG8_SA(b, h) + aoff + m * 2048 + k * 1024); } while (0)
; #define PG8_LDB(dst, b, h) do { _Pragma("unroll") for (int n = 0; n < 2; ++n) _Pragma("unroll") for (int k = 0; k < 2; ++k) dst[n][k] = *(const PG8_LAS bf16x8*)(lds + PG8_SB(b, h) + boff + n * 2048 + k * 1024); } while (0)
; #define PG8_MMA(ai, bj, At, Bt) do { __builtin_amdgcn_s_setprio(1); _Pragma("unroll") for (int m = 0; m < 4; ++m) _Pragma("unroll") for (int n = 0; n < 2; ++n) _Pragma("unroll") for (int k = 0; k < 2; ++k) \
;         acc[ai][bj][m][n] = __builtin_amdgcn_mfma_f32_16x16x32_bf16(Bt[n][k], At[m][k], acc[ai][bj][m][n], 0, 0, 0); __builtin_amdgcn_s_setprio(0); } while (0)
; #define PG8_WAIT_V(n) asm volatile("s_waitcnt vmcnt(" #n ")" ::: "memory")
; #define PG8_WAIT_L(n) asm volatile("s_waitcnt lgkmcnt(" #n ")" ::: "memory")
; #define PG8_BAR __builtin_amdgcn_s_barrier()
; #define PG8_SCHED __builtin_amdgcn_sched_barrier(0)
; template <class Epi, class Sched, bool ALIGN_EPI = false, bool SP2 = false>
; __device__ __forceinline__ void gemm_phase(PG8_LAS unsigned char* lds, const Gemm g, const Sched& S, const Epi& E) {
;     ...
;             PG8_WAIT_V(8); PG8_WAIT_L(0); PG8_BAR; PG8_MMA(1, 0, At, B0); PG8_MMA(1, 1, At, B1); PG8_BAR; PG8_SCHED;
;             PG8_LDB(B0, 1, 0); PG8_LDB(B1, 1, 1); PG8_SCHED; PG8_LDA(At, 1, 0); PG8_STAGE(PG8_SA(0, 1), a2 + hstep, voffA);
;             PG8_WAIT_V(8); PG8_WAIT_L(0); PG8_BAR; PG8_MMA(0, 0, At, B0); PG8_MMA(0, 1, At, B1); PG8_BAR; PG8_SCHED;
	s_setprio 1
	s_waitcnt lgkmcnt(0)
	v_mfma_f32_16x16x32_bf16 v[62:65], v[152:155], v[194:197], v[62:65]
	v_mfma_f32_16x16x32_bf16 v[58:61], v[160:163], v[194:197], v[58:61]
	v_mfma_f32_16x16x32_bf16 v[54:57], v[152:155], v[202:205], v[54:57]
	v_mfma_f32_16x16x32_bf16 v[46:49], v[160:163], v[202:205], v[46:49]
	v_mfma_f32_16x16x32_bf16 v[38:41], v[152:155], v[210:213], v[38:41]
	v_mfma_f32_16x16x32_bf16 v[30:33], v[160:163], v[210:213], v[30:33]
	v_mfma_f32_16x16x32_bf16 v[22:25], v[152:155], v[218:221], v[22:25]
	v_mfma_f32_16x16x32_bf16 v[14:17], v[160:163], v[218:221], v[14:17]
	v_mfma_f32_16x16x32_bf16 v[62:65], v[156:159], v[198:201], v[62:65]
	v_mfma_f32_16x16x32_bf16 v[58:61], v[174:177], v[198:201], v[58:61]
	v_mfma_f32_16x16x32_bf16 v[54:57], v[156:159], v[206:209], v[54:57]
	v_mfma_f32_16x16x32_bf16 v[46:49], v[174:177], v[206:209], v[46:49]
	v_mfma_f32_16x16x32_bf16 v[38:41], v[156:159], v[214:217], v[38:41]
	v_mfma_f32_16x16x32_bf16 v[30:33], v[174:177], v[214:217], v[30:33]
	v_mfma_f32_16x16x32_bf16 v[22:25], v[156:159], v[222:225], v[22:25]
	v_mfma_f32_16x16x32_bf16 v[14:17], v[174:177], v[222:225], v[14:17]
	v_mfma_f32_16x16x32_bf16 v[50:53], v[178:181], v[194:197], v[50:53]
	v_mfma_f32_16x16x32_bf16 v[42:45], v[186:189], v[194:197], v[42:45]
	v_mfma_f32_16x16x32_bf16 v[34:37], v[178:181], v[202:205], v[34:37]
	v_mfma_f32_16x16x32_bf16 v[26:29], v[186:189], v[202:205], v[26:29]
	v_mfma_f32_16x16x32_bf16 v[18:21], v[178:181], v[210:213], v[18:21]
	v_mfma_f32_16x16x32_bf16 v[10:13], v[186:189], v[210:213], v[10:13]
	v_mfma_f32_16x16x32_bf16 v[6:9], v[178:181], v[218:221], v[6:9]
	v_mfma_f32_16x16x32_bf16 v[2:5], v[186:189], v[218:221], v[2:5]
	v_mfma_f32_16x16x32_bf16 v[50:53], v[182:185], v[198:201], v[50:53]
	v_mfma_f32_16x16x32_bf16 v[42:45], v[190:193], v[198:201], v[42:45]
	v_mfma_f32_16x16x32_bf16 v[34:37], v[182:185], v[206:209], v[34:37]
	v_mfma_f32_16x16x32_bf16 v[26:29], v[190:193], v[206:209], v[26:29]
	v_mfma_f32_16x16x32_bf16 v[18:21], v[182:185], v[214:217], v[18:21]
	v_mfma_f32_16x16x32_bf16 v[10:13], v[190:193], v[214:217], v[10:13]
	v_mfma_f32_16x16x32_bf16 v[6:9], v[182:185], v[222:225], v[6:9]
	s_barrier
	v_mfma_f32_16x16x32_bf16 v[2:5], v[190:193], v[222:225], v[2:5]
	s_setprio 0
	s_add_i32 s64, 0, 0x18000
	v_add_u32_e32 v173, s64, v149
	s_add_i32 s65, 0, 0x1c000
	ds_read_b128 v[152:155], v173
	ds_read_b128 v[156:159], v173 offset:1024
	ds_read_b128 v[160:163], v173 offset:2048
	ds_read_b128 v[174:177], v173 offset:3072
	v_add_u32_e32 v173, s65, v149
	ds_read_b128 v[178:181], v173
	ds_read_b128 v[182:185], v173 offset:1024
	ds_read_b128 v[186:189], v173 offset:2048
	ds_read_b128 v[190:193], v173 offset:3072
	s_add_u32 s48, s48, 0x40000
	s_addc_u32 s49, s49, 0
	s_mov_b32 m0, s54
	v_lshl_add_u64 v[232:233], s[48:49], 0, v[140:141]
	ds_read_b128 v[194:197], v151 offset:32768
	ds_read_b128 v[198:201], v151 offset:33792
	ds_read_b128 v[202:205], v151 offset:34816
	ds_read_b128 v[206:209], v151 offset:35840
	ds_read_b128 v[210:213], v151 offset:36864
	ds_read_b128 v[214:217], v151 offset:37888
	ds_read_b128 v[218:221], v151 offset:38912
	ds_read_b128 v[222:225], v151 offset:39936
	global_load_lds_dwordx4 v[232:233], off
	v_lshl_add_u64 v[232:233], s[48:49], 0, v[138:139]
	s_mov_b32 m0, s55
	s_nop 0
	global_load_lds_dwordx4 v[232:233], off
	s_waitcnt vmcnt(8)
	s_waitcnt lgkmcnt(0)
	s_barrier
	s_setprio 1
	s_waitcnt lgkmcnt(0)
	v_mfma_f32_16x16x32_bf16 v[126:129], v[152:155], v[194:197], v[126:129]
	v_mfma_f32_16x16x32_bf16 v[122:125], v[160:163], v[194:197], v[122:125]
	v_mfma_f32_16x16x32_bf16 v[118:121], v[152:155], v[202:205], v[118:121]
	v_mfma_f32_16x16x32_bf16 v[110:113], v[160:163], v[202:205], v[110:113]
	v_mfma_f32_16x16x32_bf16 v[102:105], v[152:155], v[210:213], v[102:105]
	v_mfma_f32_16x16x32_bf16 v[94:97], v[160:163], v[210:213], v[94:97]
	v_mfma_f32_16x16x32_bf16 v[86:89], v[152:155], v[218:221], v[86:89]
	v_mfma_f32_16x16x32_bf16 v[78:81], v[160:163], v[218:221], v[78:81]
	v_mfma_f32_16x16x32_bf16 v[126:129], v[156:159], v[198:201], v[126:129]
	v_mfma_f32_16x16x32_bf16 v[122:125], v[174:177], v[198:201], v[122:125]
	v_mfma_f32_16x16x32_bf16 v[118:121], v[156:159], v[206:209], v[118:121]
	v_mfma_f32_16x16x32_bf16 v[110:113], v[174:177], v[206:209], v[110:113]
	v_mfma_f32_16x16x32_bf16 v[102:105], v[156:159], v[214:217], v[102:105]
	v_mfma_f32_16x16x32_bf16 v[94:97], v[174:177], v[214:217], v[94:97]
	v_mfma_f32_16x16x32_bf16 v[86:89], v[156:159], v[222:225], v[86:89]
	v_mfma_f32_16x16x32_bf16 v[78:81], v[174:177], v[222:225], v[78:81]
	v_mfma_f32_16x16x32_bf16 v[114:117], v[178:181], v[194:197], v[114:117]
	v_mfma_f32_16x16x32_bf16 v[106:109], v[186:189], v[194:197], v[106:109]
	v_mfma_f32_16x16x32_bf16 v[98:101], v[178:181], v[202:205], v[98:101]
	v_mfma_f32_16x16x32_bf16 v[90:93], v[186:189], v[202:205], v[90:93]
	v_mfma_f32_16x16x32_bf16 v[82:85], v[178:181], v[210:213], v[82:85]
	v_mfma_f32_16x16x32_bf16 v[74:77], v[186:189], v[210:213], v[74:77]
	v_mfma_f32_16x16x32_bf16 v[70:73], v[178:181], v[218:221], v[70:73]
	v_mfma_f32_16x16x32_bf16 v[66:69], v[186:189], v[218:221], v[66:69]
	v_mfma_f32_16x16x32_bf16 v[114:117], v[182:185], v[198:201], v[114:117]
	v_mfma_f32_16x16x32_bf16 v[106:109], v[190:193], v[198:201], v[106:109]
	v_mfma_f32_16x16x32_bf16 v[98:101], v[182:185], v[206:209], v[98:101]
	v_mfma_f32_16x16x32_bf16 v[90:93], v[190:193], v[206:209], v[90:93]
	v_mfma_f32_16x16x32_bf16 v[82:85], v[182:185], v[214:217], v[82:85]
	v_mfma_f32_16x16x32_bf16 v[74:77], v[190:193], v[214:217], v[74:77]
	v_mfma_f32_16x16x32_bf16 v[70:73], v[182:185], v[222:225], v[70:73]
	s_barrier
; #define PG8_STAGE(bufoff, gbase, voff) do { _Pragma("unroll") for (int _i = 0; _i < 2; ++_i) \
;         __builtin_amdgcn_global_load_lds((const unsigned*)((const char*)(gbase) + (voff)[_i]), (PG8_LAS unsigned*)(lds + (bufoff) + ldsw + _i * 8192), 16, 0, 0); } while (0)
; #define PG8_LDA(dst, b, h) do { _Pragma("unroll") for (int m = 0; m < 4; ++m) _Pragma("unroll") for (int k = 0; k < 2; ++k) dst[m][k] = *(const PG8_LAS bf16x8*)(lds + PG8_SA(b, h) + aoff + m * 2048 + k * 1024); } while (0)
; #define PG8_MMA(ai, bj, At, Bt) do { __builtin_amdgcn_s_setprio(1); _Pragma("unroll") for (int m = 0; m < 4; ++m) _Pragma("unroll") for (int n = 0; n < 2; ++n) _Pragma("unroll") for (int k = 0; k < 2; ++k) \
;         acc[ai][bj][m][n] = __builtin_amdgcn_mfma_f32_16x16x32_bf16(Bt[n][k], At[m][k], acc[ai][bj][m][n], 0, 0, 0); __builtin_amdgcn_s_setprio(0); } while (0)
; #define PG8_WAIT_V(n) asm volatile("s_waitcnt vmcnt(" #n ")" ::: "memory")
; #define PG8_WAIT_L(n) asm volatile("s_waitcnt lgkmcnt(" #n ")" ::: "memory")
; #define PG8_BAR __builtin_amdgcn_s_barrier()
; #define PG8_SCHED __builtin_amdgcn_sched_barrier(0)
; template <class Epi, class Sched, bool ALIGN_EPI = false, bool SP2 = false>
; __device__ __forceinline__ void gemm_phase(PG8_LAS unsigned char* lds, const Gemm g, const Sched& S, const Epi& E) {
;     ...
;             PG8_WAIT_V(8); PG8_WAIT_L(0); PG8_BAR; PG8_MMA(0, 0, At, B0); PG8_MMA(0, 1, At, B1); PG8_BAR; PG8_SCHED;
;             PG8_LDA(At, 1, 1); PG8_STAGE(PG8_SB(1, 0), b3, voffB); PG8_STAGE(PG8_SB(1, 1), b3 + hstep, voffB); PG8_STAGE(PG8_SA(1, 0), a3, voffA);
;             PG8_WAIT_V(8); PG8_WAIT_L(0); PG8_BAR; PG8_MMA(1, 0, At, B0); PG8_MMA(1, 1, At, B1); PG8_BAR; PG8_SCHED;
	v_mfma_f32_16x16x32_bf16 v[66:69], v[190:193], v[222:225], v[66:69]
	s_setprio 0
	s_add_i32 s48, s64, s34
	v_lshl_add_u64 v[146:147], v[146:147], 0, s[96:97]
	s_mov_b32 m0, s48
	ds_read_b128 v[194:197], v151 offset:49152
	ds_read_b128 v[198:201], v151 offset:50176
	ds_read_b128 v[202:205], v151 offset:51200
	ds_read_b128 v[206:209], v151 offset:52224
	ds_read_b128 v[210:213], v151 offset:53248
	ds_read_b128 v[214:217], v151 offset:54272
	ds_read_b128 v[218:221], v151 offset:55296
	ds_read_b128 v[222:225], v151 offset:56320
	global_load_lds_dwordx4 v[146:147], off
	s_add_i32 m0, s48, 0x2000
	s_add_u32 s46, s46, 0x40080
	v_lshl_add_u64 v[146:147], v[226:227], 0, s[96:97]
	s_addc_u32 s47, s47, 0
	s_add_i32 s48, s65, s34
	global_load_lds_dwordx4 v[146:147], off
	v_lshl_add_u64 v[146:147], s[46:47], 0, v[130:131]
	s_mov_b32 m0, s48
	s_nop 0
	global_load_lds_dwordx4 v[146:147], off
	v_lshl_add_u64 v[146:147], s[46:47], 0, v[136:137]
	s_add_i32 m0, s48, 0x2000
	s_nop 0
	global_load_lds_dwordx4 v[146:147], off
	v_lshl_add_u64 v[146:147], v[228:229], 0, s[96:97]
	s_mov_b32 m0, s56
	s_nop 0
	global_load_lds_dwordx4 v[146:147], off
	v_lshl_add_u64 v[146:147], v[230:231], 0, s[96:97]
	s_mov_b32 m0, s57
	s_nop 0
	global_load_lds_dwordx4 v[146:147], off
	s_waitcnt vmcnt(8)
	s_waitcnt lgkmcnt(0)
	s_barrier
	s_setprio 1
	s_waitcnt lgkmcnt(0)
	v_mfma_f32_16x16x32_bf16 v[62:65], v[152:155], v[194:197], v[62:65]
	v_mfma_f32_16x16x32_bf16 v[58:61], v[160:163], v[194:197], v[58:61]
	v_mfma_f32_16x16x32_bf16 v[54:57], v[152:155], v[202:205], v[54:57]
	v_mfma_f32_16x16x32_bf16 v[46:49], v[160:163], v[202:205], v[46:49]
	v_mfma_f32_16x16x32_bf16 v[38:41], v[152:155], v[210:213], v[38:41]
	v_mfma_f32_16x16x32_bf16 v[30:33], v[160:163], v[210:213], v[30:33]
	v_mfma_f32_16x16x32_bf16 v[22:25], v[152:155], v[218:221], v[22:25]
	v_mfma_f32_16x16x32_bf16 v[14:17], v[160:163], v[218:221], v[14:17]
	v_mfma_f32_16x16x32_bf16 v[62:65], v[156:159], v[198:201], v[62:65]
	v_mfma_f32_16x16x32_bf16 v[58:61], v[174:177], v[198:201], v[58:61]
	v_mfma_f32_16x16x32_bf16 v[54:57], v[156:159], v[206:209], v[54:57]
	v_mfma_f32_16x16x32_bf16 v[46:49], v[174:177], v[206:209], v[46:49]
	v_mfma_f32_16x16x32_bf16 v[38:41], v[156:159], v[214:217], v[38:41]
	v_mfma_f32_16x16x32_bf16 v[30:33], v[174:177], v[214:217], v[30:33]
	v_mfma_f32_16x16x32_bf16 v[22:25], v[156:159], v[222:225], v[22:25]
	v_mfma_f32_16x16x32_bf16 v[14:17], v[174:177], v[222:225], v[14:17]
	v_mfma_f32_16x16x32_bf16 v[50:53], v[178:181], v[194:197], v[50:53]
	v_mfma_f32_16x16x32_bf16 v[42:45], v[186:189], v[194:197], v[42:45]
	v_mfma_f32_16x16x32_bf16 v[34:37], v[178:181], v[202:205], v[34:37]
	v_mfma_f32_16x16x32_bf16 v[26:29], v[186:189], v[202:205], v[26:29]
	v_mfma_f32_16x16x32_bf16 v[18:21], v[178:181], v[210:213], v[18:21]
	v_mfma_f32_16x16x32_bf16 v[10:13], v[186:189], v[210:213], v[10:13]
	v_mfma_f32_16x16x32_bf16 v[6:9], v[178:181], v[218:221], v[6:9]
	v_mfma_f32_16x16x32_bf16 v[2:5], v[186:189], v[218:221], v[2:5]
	v_mfma_f32_16x16x32_bf16 v[50:53], v[182:185], v[198:201], v[50:53]
	v_mfma_f32_16x16x32_bf16 v[42:45], v[190:193], v[198:201], v[42:45]
	v_mfma_f32_16x16x32_bf16 v[34:37], v[182:185], v[206:209], v[34:37]
	v_mfma_f32_16x16x32_bf16 v[26:29], v[190:193], v[206:209], v[26:29]
	v_mfma_f32_16x16x32_bf16 v[18:21], v[182:185], v[214:217], v[18:21]
	v_mfma_f32_16x16x32_bf16 v[10:13], v[190:193], v[214:217], v[10:13]
	v_mfma_f32_16x16x32_bf16 v[6:9], v[182:185], v[222:225], v[6:9]
	s_barrier
	v_mfma_f32_16x16x32_bf16 v[2:5], v[190:193], v[222:225], v[2:5]
	s_setprio 0
	s_add_i32 s63, s63, 2
	s_add_u32 s44, s44, 0x100
	s_addc_u32 s45, s45, 0
	s_add_u32 s61, s61, 0x100
	s_addc_u32 s62, s62, 0
	s_cmp_gt_u32 s63, 13
	s_cbranch_scc0 .LBB0_121
	s_and_b64 vcc, exec, s[6:7]
	s_cbranch_vccz .LBB0_124
	s_barrier

; #define PG8_STAGE(bufoff, gbase, voff) do { _Pragma("unroll") for (int _i = 0; _i < 2; ++_i) \
;         __builtin_amdgcn_global_load_lds((const unsigned*)((const char*)(gbase) + (voff)[_i]), (PG8_LAS unsigned*)(lds + (bufoff) + ldsw + _i * 8192), 16, 0, 0); } while (0)
; #define PG8_LDA(dst, b, h) do { _Pragma("unroll") for (int m = 0; m < 4; ++m) _Pragma("unroll") for (int k = 0; k < 2; ++k) dst[m][k] = *(const PG8_LAS bf16x8*)(lds + PG8_SA(b, h) + aoff + m * 2048 + k * 1024); } while (0)
; #define PG8_LDB(dst, b, h) do { _Pragma("unroll") for (int n = 0; n < 2; ++n) _Pragma("unroll") for (int k = 0; k < 2; ++k) dst[n][k] = *(const PG8_LAS bf16x8*)(lds + PG8_SB(b, h) + boff + n * 2048 + k * 1024); } while (0)
; #define PG8_MMA(ai, bj, At, Bt) do { __builtin_amdgcn_s_setprio(1); _Pragma("unroll") for (int m = 0; m < 4; ++m) _Pragma("unroll") for (int n = 0; n < 2; ++n) _Pragma("unroll") for (int k = 0; k < 2; ++k) \
;         acc[ai][bj][m][n] = __builtin_amdgcn_mfma_f32_16x16x32_bf16(Bt[n][k], At[m][k], acc[ai][bj][m][n], 0, 0, 0); __builtin_amdgcn_s_setprio(0); } while (0)
; #define PG8_WAIT_V(n) asm volatile("s_waitcnt vmcnt(" #n ")" ::: "memory")
; #define PG8_WAIT_L(n) asm volatile("s_waitcnt lgkmcnt(" #n ")" ::: "memory")
; #define PG8_BAR __builtin_amdgcn_s_barrier()
; #define PG8_SCHED __builtin_amdgcn_sched_barrier(0)
; template <class Epi, class Sched, bool ALIGN_EPI = false, bool SP2 = false>
; __device__ __forceinline__ void gemm_phase(PG8_LAS unsigned char* lds, const Gemm g, const Sched& S, const Epi& E) {
;     ...
;             const bool last = (t == nt - 2);
;             const char* a1 = cA + (size_t)(t + 1) * kstep;
;             const char* a2 = last ? nA : cA + (size_t)(t + 2) * kstep; const char* b2 = last ? nB : cB + (size_t)(t + 2) * kstep;
;             const char* a3 = a2 + kstep; const char* b3 = b2 + kstep;
;             if (last && has_next) S.a_ready(nxt);
;             if constexpr (SP2) {
;             PG8_LDB(B0, 0, 0); PG8_LDB(B1, 0, 1); PG8_SCHED; PG8_LDA(At, 0, 0); PG8_STAGE(PG8_SA(1, 1), a1 + hstep, voffA);
;             PG8_WAIT_V(8); PG8_WAIT_L(0); PG8_BAR; PG8_MMA(0, 0, At, B0); PG8_MMA(0, 1, At, B1); PG8_BAR; PG8_SCHED;
;             PG8_LDA(At, 0, 1); PG8_STAGE(PG8_SB(0, 0), b2, voffB); PG8_STAGE(PG8_SB(0, 1), b2 + hstep, voffB); PG8_STAGE(PG8_SA(0, 0), a2, voffA);
.LBB0_811:
	ds_read_b128 v[130:133], v159
	ds_read_b128 v[152:155], v159 offset:1024
	ds_read_b128 v[166:169], v159 offset:2048
	ds_read_b128 v[170:173], v159 offset:3072
	ds_read_b128 v[174:177], v160
	ds_read_b128 v[178:181], v160 offset:1024
	ds_read_b128 v[182:185], v160 offset:2048
	ds_read_b128 v[186:189], v160 offset:3072
	s_add_u32 s42, s4, 0xfffc0080
	s_addc_u32 s43, s5, -1
	s_cmp_eq_u32 s47, 12
	s_cselect_b32 s45, s35, s43
	s_cselect_b32 s44, s34, s42
	s_cselect_b32 s43, s6, s46
	s_cselect_b32 s42, s23, s25
	v_lshl_add_u64 v[162:163], s[4:5], 0, v[144:145]
	s_add_i32 m0, s39, 0xc000
	ds_read_b128 v[190:193], v161
	ds_read_b128 v[194:197], v161 offset:1024
	ds_read_b128 v[198:201], v161 offset:2048
	ds_read_b128 v[202:205], v161 offset:3072
	ds_read_b128 v[206:209], v161 offset:4096
	ds_read_b128 v[210:213], v161 offset:5120
	ds_read_b128 v[214:217], v161 offset:6144
	ds_read_b128 v[218:221], v161 offset:7168
	global_load_lds_dwordx4 v[162:163], off
	v_lshl_add_u64 v[162:163], s[4:5], 0, v[146:147]
	s_add_i32 m0, s39, 0xe000
	s_nop 0
	global_load_lds_dwordx4 v[162:163], off
	s_waitcnt vmcnt(8)
	s_waitcnt lgkmcnt(0)
	s_barrier
	s_setprio 1
	s_waitcnt lgkmcnt(0)
	v_mfma_f32_16x16x32_bf16 v[126:129], v[130:133], v[190:193], v[126:129]
	v_mfma_f32_16x16x32_bf16 v[122:125], v[166:169], v[190:193], v[122:125]
	v_mfma_f32_16x16x32_bf16 v[110:113], v[130:133], v[198:201], v[110:113]
	v_mfma_f32_16x16x32_bf16 v[106:109], v[166:169], v[198:201], v[106:109]
	v_mfma_f32_16x16x32_bf16 v[94:97], v[130:133], v[206:209], v[94:97]
	v_mfma_f32_16x16x32_bf16 v[90:93], v[166:169], v[206:209], v[90:93]
	v_mfma_f32_16x16x32_bf16 v[78:81], v[130:133], v[214:217], v[78:81]
	v_mfma_f32_16x16x32_bf16 v[74:77], v[166:169], v[214:217], v[74:77]
	v_mfma_f32_16x16x32_bf16 v[126:129], v[152:155], v[194:197], v[126:129]
	v_mfma_f32_16x16x32_bf16 v[122:125], v[170:173], v[194:197], v[122:125]
	v_mfma_f32_16x16x32_bf16 v[110:113], v[152:155], v[202:205], v[110:113]
	v_mfma_f32_16x16x32_bf16 v[106:109], v[170:173], v[202:205], v[106:109]
	v_mfma_f32_16x16x32_bf16 v[94:97], v[152:155], v[210:213], v[94:97]
	v_mfma_f32_16x16x32_bf16 v[90:93], v[170:173], v[210:213], v[90:93]
	v_mfma_f32_16x16x32_bf16 v[78:81], v[152:155], v[218:221], v[78:81]
	v_mfma_f32_16x16x32_bf16 v[74:77], v[170:173], v[218:221], v[74:77]
	v_mfma_f32_16x16x32_bf16 v[118:121], v[174:177], v[190:193], v[118:121]
	v_mfma_f32_16x16x32_bf16 v[114:117], v[182:185], v[190:193], v[114:117]
	v_mfma_f32_16x16x32_bf16 v[102:105], v[174:177], v[198:201], v[102:105]
	v_mfma_f32_16x16x32_bf16 v[98:101], v[182:185], v[198:201], v[98:101]
	v_mfma_f32_16x16x32_bf16 v[86:89], v[174:177], v[206:209], v[86:89]
	v_mfma_f32_16x16x32_bf16 v[82:85], v[182:185], v[206:209], v[82:85]
	v_mfma_f32_16x16x32_bf16 v[70:73], v[174:177], v[214:217], v[70:73]
	v_mfma_f32_16x16x32_bf16 v[66:69], v[182:185], v[214:217], v[66:69]
	v_mfma_f32_16x16x32_bf16 v[118:121], v[178:181], v[194:197], v[118:121]
	v_mfma_f32_16x16x32_bf16 v[114:117], v[186:189], v[194:197], v[114:117]
	v_mfma_f32_16x16x32_bf16 v[102:105], v[178:181], v[202:205], v[102:105]
	v_mfma_f32_16x16x32_bf16 v[98:101], v[186:189], v[202:205], v[98:101]
	v_mfma_f32_16x16x32_bf16 v[86:89], v[178:181], v[210:213], v[86:89]
	v_mfma_f32_16x16x32_bf16 v[82:85], v[186:189], v[210:213], v[82:85]
	v_mfma_f32_16x16x32_bf16 v[70:73], v[178:181], v[218:221], v[70:73]
	s_barrier
	v_mfma_f32_16x16x32_bf16 v[66:69], v[186:189], v[218:221], v[66:69]
	s_setprio 0
	s_add_i32 s61, s54, s33
	v_lshl_add_u64 v[162:163], s[42:43], 0, v[136:137]
	s_mov_b32 m0, s61
	ds_read_b128 v[190:193], v161 offset:16384
	ds_read_b128 v[194:197], v161 offset:17408
	ds_read_b128 v[198:201], v161 offset:18432
	ds_read_b128 v[202:205], v161 offset:19456
	ds_read_b128 v[206:209], v161 offset:20480
	ds_read_b128 v[210:213], v161 offset:21504
	ds_read_b128 v[214:217], v161 offset:22528
	ds_read_b128 v[218:221], v161 offset:23552
	global_load_lds_dwordx4 v[162:163], off
	s_add_i32 m0, s61, 0x2000
	s_add_u32 s62, s42, 0x40000
	v_lshl_add_u64 v[222:223], s[42:43], 0, v[140:141]
	s_addc_u32 s63, s43, 0
	s_add_i32 s61, s55, s33
	global_load_lds_dwordx4 v[222:223], off
	v_lshl_add_u64 v[224:225], s[62:63], 0, v[136:137]
	s_mov_b32 m0, s61
	v_lshl_add_u64 v[226:227], s[44:45], 0, v[138:139]
	global_load_lds_dwordx4 v[224:225], off
	v_lshl_add_u64 v[224:225], s[62:63], 0, v[140:141]
	s_add_i32 m0, s61, 0x2000
	s_nop 0
	global_load_lds_dwordx4 v[224:225], off
	v_lshl_add_u64 v[224:225], s[44:45], 0, v[134:135]
	s_mov_b32 m0, s39
	s_nop 0
	global_load_lds_dwordx4 v[224:225], off
	s_mov_b32 m0, s49
	s_nop 0
	global_load_lds_dwordx4 v[226:227], off
	s_waitcnt vmcnt(8)
	s_waitcnt lgkmcnt(0)
	s_barrier
; #define PG8_STAGE(bufoff, gbase, voff) do { _Pragma("unroll") for (int _i = 0; _i < 2; ++_i) \
;         __builtin_amdgcn_global_load_lds((const unsigned*)((const char*)(gbase) + (voff)[_i]), (PG8_LAS unsigned*)(lds + (bufoff) + ldsw + _i * 8192), 16, 0, 0); } while (0)
; #define PG8_LDA(dst, b, h) do { _Pragma("unroll") for (int m = 0; m < 4; ++m) _Pragma("unroll") for (int k = 0; k < 2; ++k) dst[m][k] = *(const PG8_LAS bf16x8*)(lds + PG8_SA(b, h) + aoff + m * 2048 + k * 1024); } while (0)
; #define PG8_LDB(dst, b, h) do { _Pragma("unroll") for (int n = 0; n < 2; ++n) _Pragma("unroll") for (int k = 0; k < 2; ++k) dst[n][k] = *(const PG8_LAS bf16x8*)(lds + PG8_SB(b, h) + boff + n * 2048 + k * 1024); } while (0)
; #define PG8_MMA(ai, bj, At, Bt) do { __builtin_amdgcn_s_setprio(1); _Pragma("unroll") for (int m = 0; m < 4; ++m) _Pragma("unroll") for (int n = 0; n < 2; ++n) _Pragma("unroll") for (int k = 0; k < 2; ++k) \
;         acc[ai][bj][m][n] = __builtin_amdgcn_mfma_f32_16x16x32_bf16(Bt[n][k], At[m][k], acc[ai][bj][m][n], 0, 0, 0); __builtin_amdgcn_s_setprio(0); } while (0)
; #define PG8_WAIT_V(n) asm volatile("s_waitcnt vmcnt(" #n ")" ::: "memory")
; #define PG8_WAIT_L(n) asm volatile("s_waitcnt lgkmcnt(" #n ")" ::: "memory")
; #define PG8_BAR __builtin_amdgcn_s_barrier()
; #define PG8_SCHED __builtin_amdgcn_sched_barrier(0)
; template <class Epi, class Sched, bool ALIGN_EPI = false, bool SP2 = false>
; __device__ __forceinline__ void gemm_phase(PG8_LAS unsigned char* lds, const Gemm g, const Sched& S, const Epi& E) {
;     ...
;             PG8_WAIT_V(8); PG8_WAIT_L(0); PG8_BAR; PG8_MMA(1, 0, At, B0); PG8_MMA(1, 1, At, B1); PG8_BAR; PG8_SCHED;
;             PG8_LDB(B0, 1, 0); PG8_LDB(B1, 1, 1); PG8_SCHED; PG8_LDA(At, 1, 0); PG8_STAGE(PG8_SA(0, 1), a2 + hstep, voffA);
;             PG8_WAIT_V(8); PG8_WAIT_L(0); PG8_BAR; PG8_MMA(0, 0, At, B0); PG8_MMA(0, 1, At, B1); PG8_BAR; PG8_SCHED;
	s_setprio 1
	s_waitcnt lgkmcnt(0)
	v_mfma_f32_16x16x32_bf16 v[62:65], v[130:133], v[190:193], v[62:65]
	v_mfma_f32_16x16x32_bf16 v[58:61], v[166:169], v[190:193], v[58:61]
	v_mfma_f32_16x16x32_bf16 v[46:49], v[130:133], v[198:201], v[46:49]
	v_mfma_f32_16x16x32_bf16 v[42:45], v[166:169], v[198:201], v[42:45]
	v_mfma_f32_16x16x32_bf16 v[30:33], v[130:133], v[206:209], v[30:33]
	v_mfma_f32_16x16x32_bf16 v[26:29], v[166:169], v[206:209], v[26:29]
	v_mfma_f32_16x16x32_bf16 v[14:17], v[130:133], v[214:217], v[14:17]
	v_mfma_f32_16x16x32_bf16 v[10:13], v[166:169], v[214:217], v[10:13]
	v_mfma_f32_16x16x32_bf16 v[62:65], v[152:155], v[194:197], v[62:65]
	v_mfma_f32_16x16x32_bf16 v[58:61], v[170:173], v[194:197], v[58:61]
	v_mfma_f32_16x16x32_bf16 v[46:49], v[152:155], v[202:205], v[46:49]
	v_mfma_f32_16x16x32_bf16 v[42:45], v[170:173], v[202:205], v[42:45]
	v_mfma_f32_16x16x32_bf16 v[30:33], v[152:155], v[210:213], v[30:33]
	v_mfma_f32_16x16x32_bf16 v[26:29], v[170:173], v[210:213], v[26:29]
	v_mfma_f32_16x16x32_bf16 v[14:17], v[152:155], v[218:221], v[14:17]
	v_mfma_f32_16x16x32_bf16 v[10:13], v[170:173], v[218:221], v[10:13]
	v_mfma_f32_16x16x32_bf16 v[54:57], v[174:177], v[190:193], v[54:57]
	v_mfma_f32_16x16x32_bf16 v[50:53], v[182:185], v[190:193], v[50:53]
	v_mfma_f32_16x16x32_bf16 v[38:41], v[174:177], v[198:201], v[38:41]
	v_mfma_f32_16x16x32_bf16 v[34:37], v[182:185], v[198:201], v[34:37]
	v_mfma_f32_16x16x32_bf16 v[22:25], v[174:177], v[206:209], v[22:25]
	v_mfma_f32_16x16x32_bf16 v[18:21], v[182:185], v[206:209], v[18:21]
	v_mfma_f32_16x16x32_bf16 v[6:9], v[174:177], v[214:217], v[6:9]
	v_mfma_f32_16x16x32_bf16 v[2:5], v[182:185], v[214:217], v[2:5]
	v_mfma_f32_16x16x32_bf16 v[54:57], v[178:181], v[194:197], v[54:57]
	v_mfma_f32_16x16x32_bf16 v[50:53], v[186:189], v[194:197], v[50:53]
	v_mfma_f32_16x16x32_bf16 v[38:41], v[178:181], v[202:205], v[38:41]
	v_mfma_f32_16x16x32_bf16 v[34:37], v[186:189], v[202:205], v[34:37]
	v_mfma_f32_16x16x32_bf16 v[22:25], v[178:181], v[210:213], v[22:25]
	v_mfma_f32_16x16x32_bf16 v[18:21], v[186:189], v[210:213], v[18:21]
	v_mfma_f32_16x16x32_bf16 v[6:9], v[178:181], v[218:221], v[6:9]
	s_barrier
	v_mfma_f32_16x16x32_bf16 v[2:5], v[186:189], v[218:221], v[2:5]
	s_setprio 0
	s_add_i32 s61, 0, 0x18000
	v_add_u32_e32 v142, s61, v157
	s_add_i32 s62, 0, 0x1c000
	ds_read_b128 v[130:133], v142
	ds_read_b128 v[152:155], v142 offset:1024
	ds_read_b128 v[166:169], v142 offset:2048
	ds_read_b128 v[170:173], v142 offset:3072
	v_add_u32_e32 v142, s62, v157
	ds_read_b128 v[174:177], v142
	ds_read_b128 v[178:181], v142 offset:1024
	ds_read_b128 v[182:185], v142 offset:2048
	ds_read_b128 v[186:189], v142 offset:3072
	s_add_u32 s44, s44, 0x40000
	s_addc_u32 s45, s45, 0
	s_mov_b32 m0, s50
	v_lshl_add_u64 v[228:229], s[44:45], 0, v[134:135]
	ds_read_b128 v[190:193], v161 offset:32768
	ds_read_b128 v[194:197], v161 offset:33792
	ds_read_b128 v[198:201], v161 offset:34816
	ds_read_b128 v[202:205], v161 offset:35840
	ds_read_b128 v[206:209], v161 offset:36864
	ds_read_b128 v[210:213], v161 offset:37888
	ds_read_b128 v[214:217], v161 offset:38912
	ds_read_b128 v[218:221], v161 offset:39936
	global_load_lds_dwordx4 v[228:229], off
	v_lshl_add_u64 v[228:229], s[44:45], 0, v[138:139]
	s_mov_b32 m0, s51
	s_nop 0
	global_load_lds_dwordx4 v[228:229], off
	s_waitcnt vmcnt(8)
	s_waitcnt lgkmcnt(0)
	s_barrier
	s_setprio 1
	s_waitcnt lgkmcnt(0)
	v_mfma_f32_16x16x32_bf16 v[126:129], v[130:133], v[190:193], v[126:129]
	v_mfma_f32_16x16x32_bf16 v[122:125], v[166:169], v[190:193], v[122:125]
	v_mfma_f32_16x16x32_bf16 v[110:113], v[130:133], v[198:201], v[110:113]
	v_mfma_f32_16x16x32_bf16 v[106:109], v[166:169], v[198:201], v[106:109]
	v_mfma_f32_16x16x32_bf16 v[94:97], v[130:133], v[206:209], v[94:97]
	v_mfma_f32_16x16x32_bf16 v[90:93], v[166:169], v[206:209], v[90:93]
	v_mfma_f32_16x16x32_bf16 v[78:81], v[130:133], v[214:217], v[78:81]
	v_mfma_f32_16x16x32_bf16 v[74:77], v[166:169], v[214:217], v[74:77]
	v_mfma_f32_16x16x32_bf16 v[126:129], v[152:155], v[194:197], v[126:129]
	v_mfma_f32_16x16x32_bf16 v[122:125], v[170:173], v[194:197], v[122:125]
	v_mfma_f32_16x16x32_bf16 v[110:113], v[152:155], v[202:205], v[110:113]
	v_mfma_f32_16x16x32_bf16 v[106:109], v[170:173], v[202:205], v[106:109]
	v_mfma_f32_16x16x32_bf16 v[94:97], v[152:155], v[210:213], v[94:97]
	v_mfma_f32_16x16x32_bf16 v[90:93], v[170:173], v[210:213], v[90:93]
	v_mfma_f32_16x16x32_bf16 v[78:81], v[152:155], v[218:221], v[78:81]
	v_mfma_f32_16x16x32_bf16 v[74:77], v[170:173], v[218:221], v[74:77]
	v_mfma_f32_16x16x32_bf16 v[118:121], v[174:177], v[190:193], v[118:121]
	v_mfma_f32_16x16x32_bf16 v[114:117], v[182:185], v[190:193], v[114:117]
	v_mfma_f32_16x16x32_bf16 v[102:105], v[174:177], v[198:201], v[102:105]
	v_mfma_f32_16x16x32_bf16 v[98:101], v[182:185], v[198:201], v[98:101]
	v_mfma_f32_16x16x32_bf16 v[86:89], v[174:177], v[206:209], v[86:89]
	v_mfma_f32_16x16x32_bf16 v[82:85], v[182:185], v[206:209], v[82:85]
	v_mfma_f32_16x16x32_bf16 v[70:73], v[174:177], v[214:217], v[70:73]
	v_mfma_f32_16x16x32_bf16 v[66:69], v[182:185], v[214:217], v[66:69]
	v_mfma_f32_16x16x32_bf16 v[118:121], v[178:181], v[194:197], v[118:121]
	v_mfma_f32_16x16x32_bf16 v[114:117], v[186:189], v[194:197], v[114:117]
	v_mfma_f32_16x16x32_bf16 v[102:105], v[178:181], v[202:205], v[102:105]
	v_mfma_f32_16x16x32_bf16 v[98:101], v[186:189], v[202:205], v[98:101]
	v_mfma_f32_16x16x32_bf16 v[86:89], v[178:181], v[210:213], v[86:89]
	v_mfma_f32_16x16x32_bf16 v[82:85], v[186:189], v[210:213], v[82:85]
	v_mfma_f32_16x16x32_bf16 v[70:73], v[178:181], v[218:221], v[70:73]
	s_barrier
; #define PG8_STAGE(bufoff, gbase, voff) do { _Pragma("unroll") for (int _i = 0; _i < 2; ++_i) \
;         __builtin_amdgcn_global_load_lds((const unsigned*)((const char*)(gbase) + (voff)[_i]), (PG8_LAS unsigned*)(lds + (bufoff) + ldsw + _i * 8192), 16, 0, 0); } while (0)
; #define PG8_LDA(dst, b, h) do { _Pragma("unroll") for (int m = 0; m < 4; ++m) _Pragma("unroll") for (int k = 0; k < 2; ++k) dst[m][k] = *(const PG8_LAS bf16x8*)(lds + PG8_SA(b, h) + aoff + m * 2048 + k * 1024); } while (0)
; #define PG8_MMA(ai, bj, At, Bt) do { __builtin_amdgcn_s_setprio(1); _Pragma("unroll") for (int m = 0; m < 4; ++m) _Pragma("unroll") for (int n = 0; n < 2; ++n) _Pragma("unroll") for (int k = 0; k < 2; ++k) \
;         acc[ai][bj][m][n] = __builtin_amdgcn_mfma_f32_16x16x32_bf16(Bt[n][k], At[m][k], acc[ai][bj][m][n], 0, 0, 0); __builtin_amdgcn_s_setprio(0); } while (0)
; #define PG8_WAIT_V(n) asm volatile("s_waitcnt vmcnt(" #n ")" ::: "memory")
; #define PG8_WAIT_L(n) asm volatile("s_waitcnt lgkmcnt(" #n ")" ::: "memory")
; #define PG8_BAR __builtin_amdgcn_s_barrier()
; #define PG8_SCHED __builtin_amdgcn_sched_barrier(0)
; template <class Epi, class Sched, bool ALIGN_EPI = false, bool SP2 = false>
; __device__ __forceinline__ void gemm_phase(PG8_LAS unsigned char* lds, const Gemm g, const Sched& S, const Epi& E) {
;     ...
;             PG8_WAIT_V(8); PG8_WAIT_L(0); PG8_BAR; PG8_MMA(0, 0, At, B0); PG8_MMA(0, 1, At, B1); PG8_BAR; PG8_SCHED;
;             PG8_LDA(At, 1, 1); PG8_STAGE(PG8_SB(1, 0), b3, voffB); PG8_STAGE(PG8_SB(1, 1), b3 + hstep, voffB); PG8_STAGE(PG8_SA(1, 0), a3, voffA);
;             PG8_WAIT_V(8); PG8_WAIT_L(0); PG8_BAR; PG8_MMA(1, 0, At, B0); PG8_MMA(1, 1, At, B1); PG8_BAR; PG8_SCHED;
	v_mfma_f32_16x16x32_bf16 v[66:69], v[186:189], v[218:221], v[66:69]
	s_setprio 0
	s_add_i32 s44, s61, s33
	v_lshl_add_u64 v[162:163], v[162:163], 0, s[12:13]
	s_mov_b32 m0, s44
	ds_read_b128 v[190:193], v161 offset:49152
	ds_read_b128 v[194:197], v161 offset:50176
	ds_read_b128 v[198:201], v161 offset:51200
	ds_read_b128 v[202:205], v161 offset:52224
	ds_read_b128 v[206:209], v161 offset:53248
	ds_read_b128 v[210:213], v161 offset:54272
	ds_read_b128 v[214:217], v161 offset:55296
	ds_read_b128 v[218:221], v161 offset:56320
	global_load_lds_dwordx4 v[162:163], off
	s_add_i32 m0, s44, 0x2000
	s_add_u32 s42, s42, 0x40080
	v_lshl_add_u64 v[162:163], v[222:223], 0, s[12:13]
	s_addc_u32 s43, s43, 0
	s_add_i32 s44, s62, s33
	global_load_lds_dwordx4 v[162:163], off
	v_lshl_add_u64 v[162:163], s[42:43], 0, v[136:137]
	s_mov_b32 m0, s44
	s_nop 0
	global_load_lds_dwordx4 v[162:163], off
	v_lshl_add_u64 v[162:163], s[42:43], 0, v[140:141]
	s_add_i32 m0, s44, 0x2000
	s_nop 0
	global_load_lds_dwordx4 v[162:163], off
	v_lshl_add_u64 v[162:163], v[224:225], 0, s[12:13]
	s_mov_b32 m0, s52
	s_nop 0
	global_load_lds_dwordx4 v[162:163], off
	v_lshl_add_u64 v[162:163], v[226:227], 0, s[12:13]
	s_mov_b32 m0, s53
	s_nop 0
	global_load_lds_dwordx4 v[162:163], off
	s_waitcnt vmcnt(8)
	s_waitcnt lgkmcnt(0)
	s_barrier
	s_setprio 1
	s_waitcnt lgkmcnt(0)
	v_mfma_f32_16x16x32_bf16 v[62:65], v[130:133], v[190:193], v[62:65]
	v_mfma_f32_16x16x32_bf16 v[58:61], v[166:169], v[190:193], v[58:61]
	v_mfma_f32_16x16x32_bf16 v[46:49], v[130:133], v[198:201], v[46:49]
	v_mfma_f32_16x16x32_bf16 v[42:45], v[166:169], v[198:201], v[42:45]
	v_mfma_f32_16x16x32_bf16 v[30:33], v[130:133], v[206:209], v[30:33]
	v_mfma_f32_16x16x32_bf16 v[26:29], v[166:169], v[206:209], v[26:29]
	v_mfma_f32_16x16x32_bf16 v[14:17], v[130:133], v[214:217], v[14:17]
	v_mfma_f32_16x16x32_bf16 v[10:13], v[166:169], v[214:217], v[10:13]
	v_mfma_f32_16x16x32_bf16 v[62:65], v[152:155], v[194:197], v[62:65]
	v_mfma_f32_16x16x32_bf16 v[58:61], v[170:173], v[194:197], v[58:61]
	v_mfma_f32_16x16x32_bf16 v[46:49], v[152:155], v[202:205], v[46:49]
	v_mfma_f32_16x16x32_bf16 v[42:45], v[170:173], v[202:205], v[42:45]
	v_mfma_f32_16x16x32_bf16 v[30:33], v[152:155], v[210:213], v[30:33]
	v_mfma_f32_16x16x32_bf16 v[26:29], v[170:173], v[210:213], v[26:29]
	v_mfma_f32_16x16x32_bf16 v[14:17], v[152:155], v[218:221], v[14:17]
	v_mfma_f32_16x16x32_bf16 v[10:13], v[170:173], v[218:221], v[10:13]
	v_mfma_f32_16x16x32_bf16 v[54:57], v[174:177], v[190:193], v[54:57]
	v_mfma_f32_16x16x32_bf16 v[50:53], v[182:185], v[190:193], v[50:53]
	v_mfma_f32_16x16x32_bf16 v[38:41], v[174:177], v[198:201], v[38:41]
	v_mfma_f32_16x16x32_bf16 v[34:37], v[182:185], v[198:201], v[34:37]
	v_mfma_f32_16x16x32_bf16 v[22:25], v[174:177], v[206:209], v[22:25]
	v_mfma_f32_16x16x32_bf16 v[18:21], v[182:185], v[206:209], v[18:21]
	v_mfma_f32_16x16x32_bf16 v[6:9], v[174:177], v[214:217], v[6:9]
	v_mfma_f32_16x16x32_bf16 v[2:5], v[182:185], v[214:217], v[2:5]
	v_mfma_f32_16x16x32_bf16 v[54:57], v[178:181], v[194:197], v[54:57]
	v_mfma_f32_16x16x32_bf16 v[50:53], v[186:189], v[194:197], v[50:53]
	v_mfma_f32_16x16x32_bf16 v[38:41], v[178:181], v[202:205], v[38:41]
	v_mfma_f32_16x16x32_bf16 v[34:37], v[186:189], v[202:205], v[34:37]
	v_mfma_f32_16x16x32_bf16 v[22:25], v[178:181], v[210:213], v[22:25]
	v_mfma_f32_16x16x32_bf16 v[18:21], v[186:189], v[210:213], v[18:21]
	v_mfma_f32_16x16x32_bf16 v[6:9], v[178:181], v[218:221], v[6:9]
	s_barrier
	v_mfma_f32_16x16x32_bf16 v[2:5], v[186:189], v[218:221], v[2:5]
	s_setprio 0
	s_add_i32 s47, s47, 2
	s_add_u32 s4, s4, 0x100
	s_addc_u32 s5, s5, 0
	s_add_u32 s25, s25, 0x100
	s_addc_u32 s46, s46, 0
	s_cmp_gt_u32 s47, 13
	s_cbranch_scc0 .LBB0_811
	s_and_b64 vcc, exec, s[14:15]
	s_cbranch_vccz .LBB0_814
	s_barrier

; #define PG8_STAGE(bufoff, gbase, voff) do { _Pragma("unroll") for (int _i = 0; _i < 2; ++_i) \
;         __builtin_amdgcn_global_load_lds((const unsigned*)((const char*)(gbase) + (voff)[_i]), (PG8_LAS unsigned*)(lds + (bufoff) + ldsw + _i * 8192), 16, 0, 0); } while (0)
; #define PG8_LDA(dst, b, h) do { _Pragma("unroll") for (int m = 0; m < 4; ++m) _Pragma("unroll") for (int k = 0; k < 2; ++k) dst[m][k] = *(const PG8_LAS bf16x8*)(lds + PG8_SA(b, h) + aoff + m * 2048 + k * 1024); } while (0)
; #define PG8_LDB(dst, b, h) do { _Pragma("unroll") for (int n = 0; n < 2; ++n) _Pragma("unroll") for (int k = 0; k < 2; ++k) dst[n][k] = *(const PG8_LAS bf16x8*)(lds + PG8_SB(b, h) + boff + n * 2048 + k * 1024); } while (0)
; #define PG8_MMA(ai, bj, At, Bt) do { __builtin_amdgcn_s_setprio(1); _Pragma("unroll") for (int m = 0; m < 4; ++m) _Pragma("unroll") for (int n = 0; n < 2; ++n) _Pragma("unroll") for (int k = 0; k < 2; ++k) \
;         acc[ai][bj][m][n] = __builtin_amdgcn_mfma_f32_16x16x32_bf16(Bt[n][k], At[m][k], acc[ai][bj][m][n], 0, 0, 0); __builtin_amdgcn_s_setprio(0); } while (0)
; #define PG8_WAIT_V(n) asm volatile("s_waitcnt vmcnt(" #n ")" ::: "memory")
; #define PG8_BAR __builtin_amdgcn_s_barrier()
; template <class Epi, class Sched, bool ALIGN_EPI = false, bool SP2 = false>
; __device__ __forceinline__ void gemm_phase(PG8_LAS unsigned char* lds, const Gemm g, const Sched& S, const Epi& E) {
;     ...
;         for (int t = 0; t < nt; t += 2) {
;             const bool last = (t == nt - 2);
;             const char* a1 = cA + (size_t)(t + 1) * kstep;
;             const char* a2 = last ? nA : cA + (size_t)(t + 2) * kstep; const char* b2 = last ? nB : cB + (size_t)(t + 2) * kstep;
;             const char* a3 = a2 + kstep; const char* b3 = b2 + kstep;
;             if (last && has_next) S.a_ready(nxt);
;             if constexpr (SP2) {
;             PG8_LDB(B0, 0, 0); PG8_LDB(B1, 0, 1); PG8_SCHED; PG8_LDA(At, 0, 0); PG8_STAGE(PG8_SA(1, 1), a1 + hstep, voffA);
;             PG8_WAIT_V(8); PG8_WAIT_L(0); PG8_BAR; PG8_MMA(0, 0, At, B0); PG8_MMA(0, 1, At, B1); PG8_BAR; PG8_SCHED;
;             PG8_LDA(At, 0, 1); PG8_STAGE(PG8_SB(0, 0), b2, voffB); PG8_STAGE(PG8_SB(0, 1), b2 + hstep, voffB); PG8_STAGE(PG8_SA(0, 0), a2, voffA);
;             PG8_WAIT_V(8); PG8_WAIT_L(0); PG8_BAR; PG8_MMA(1, 0, At, B0); PG8_MMA(1, 1, At, B1); PG8_BAR; PG8_SCHED;
.LBB0_884:
	ds_read_b128 v[130:133], v159
	ds_read_b128 v[146:149], v159 offset:1024
	ds_read_b128 v[150:153], v159 offset:2048
	ds_read_b128 v[162:165], v159 offset:3072
	ds_read_b128 v[166:169], v160
	ds_read_b128 v[170:173], v160 offset:1024
	ds_read_b128 v[174:177], v160 offset:2048
	ds_read_b128 v[178:181], v160 offset:3072
	s_add_u32 s46, s44, 0xfffc0080
	s_addc_u32 s47, s45, -1
	s_cmp_eq_u32 s60, 12
	s_cselect_b32 s49, s35, s47
	s_cselect_b32 s48, s34, s46
	s_cselect_b32 s47, s17, s59
	s_cselect_b32 s46, s19, s58
	v_lshl_add_u64 v[214:215], s[44:45], 0, v[142:143]
	s_add_i32 m0, s50, 0xc000
	ds_read_b128 v[182:185], v161
	ds_read_b128 v[186:189], v161 offset:1024
	ds_read_b128 v[190:193], v161 offset:2048
	ds_read_b128 v[194:197], v161 offset:3072
	ds_read_b128 v[198:201], v161 offset:4096
	ds_read_b128 v[202:205], v161 offset:5120
	ds_read_b128 v[206:209], v161 offset:6144
	ds_read_b128 v[210:213], v161 offset:7168
	global_load_lds_dwordx4 v[214:215], off
	v_lshl_add_u64 v[214:215], s[44:45], 0, v[144:145]
	s_add_i32 m0, s50, 0xe000
	s_nop 0
	global_load_lds_dwordx4 v[214:215], off
	s_waitcnt vmcnt(8)
	s_waitcnt lgkmcnt(0)
	s_barrier
	s_setprio 1
	s_waitcnt lgkmcnt(0)
	v_mfma_f32_16x16x32_bf16 v[126:129], v[130:133], v[182:185], v[126:129]
	v_mfma_f32_16x16x32_bf16 v[122:125], v[150:153], v[182:185], v[122:125]
	v_mfma_f32_16x16x32_bf16 v[110:113], v[130:133], v[190:193], v[110:113]
	v_mfma_f32_16x16x32_bf16 v[106:109], v[150:153], v[190:193], v[106:109]
	v_mfma_f32_16x16x32_bf16 v[94:97], v[130:133], v[198:201], v[94:97]
	v_mfma_f32_16x16x32_bf16 v[90:93], v[150:153], v[198:201], v[90:93]
	v_mfma_f32_16x16x32_bf16 v[78:81], v[130:133], v[206:209], v[78:81]
	v_mfma_f32_16x16x32_bf16 v[74:77], v[150:153], v[206:209], v[74:77]
	v_mfma_f32_16x16x32_bf16 v[126:129], v[146:149], v[186:189], v[126:129]
	v_mfma_f32_16x16x32_bf16 v[122:125], v[162:165], v[186:189], v[122:125]
	v_mfma_f32_16x16x32_bf16 v[110:113], v[146:149], v[194:197], v[110:113]
	v_mfma_f32_16x16x32_bf16 v[106:109], v[162:165], v[194:197], v[106:109]
	v_mfma_f32_16x16x32_bf16 v[94:97], v[146:149], v[202:205], v[94:97]
	v_mfma_f32_16x16x32_bf16 v[90:93], v[162:165], v[202:205], v[90:93]
	v_mfma_f32_16x16x32_bf16 v[78:81], v[146:149], v[210:213], v[78:81]
	v_mfma_f32_16x16x32_bf16 v[74:77], v[162:165], v[210:213], v[74:77]
	v_mfma_f32_16x16x32_bf16 v[118:121], v[166:169], v[182:185], v[118:121]
	v_mfma_f32_16x16x32_bf16 v[114:117], v[174:177], v[182:185], v[114:117]
	v_mfma_f32_16x16x32_bf16 v[102:105], v[166:169], v[190:193], v[102:105]
	v_mfma_f32_16x16x32_bf16 v[98:101], v[174:177], v[190:193], v[98:101]
	v_mfma_f32_16x16x32_bf16 v[86:89], v[166:169], v[198:201], v[86:89]
	v_mfma_f32_16x16x32_bf16 v[82:85], v[174:177], v[198:201], v[82:85]
	v_mfma_f32_16x16x32_bf16 v[70:73], v[166:169], v[206:209], v[70:73]
	v_mfma_f32_16x16x32_bf16 v[66:69], v[174:177], v[206:209], v[66:69]
	v_mfma_f32_16x16x32_bf16 v[118:121], v[170:173], v[186:189], v[118:121]
	v_mfma_f32_16x16x32_bf16 v[114:117], v[178:181], v[186:189], v[114:117]
	v_mfma_f32_16x16x32_bf16 v[102:105], v[170:173], v[194:197], v[102:105]
	v_mfma_f32_16x16x32_bf16 v[98:101], v[178:181], v[194:197], v[98:101]
	v_mfma_f32_16x16x32_bf16 v[86:89], v[170:173], v[202:205], v[86:89]
	v_mfma_f32_16x16x32_bf16 v[82:85], v[178:181], v[202:205], v[82:85]
	v_mfma_f32_16x16x32_bf16 v[70:73], v[170:173], v[210:213], v[70:73]
	s_barrier
	v_mfma_f32_16x16x32_bf16 v[66:69], v[178:181], v[210:213], v[66:69]
	s_setprio 0
	s_add_i32 s61, s56, s33
	v_lshl_add_u64 v[214:215], s[46:47], 0, v[138:139]
	s_mov_b32 m0, s61
	ds_read_b128 v[182:185], v161 offset:16384
	ds_read_b128 v[186:189], v161 offset:17408
	ds_read_b128 v[190:193], v161 offset:18432
	ds_read_b128 v[194:197], v161 offset:19456
	ds_read_b128 v[198:201], v161 offset:20480
	ds_read_b128 v[202:205], v161 offset:21504
	ds_read_b128 v[206:209], v161 offset:22528
	ds_read_b128 v[210:213], v161 offset:23552
	global_load_lds_dwordx4 v[214:215], off
	s_add_i32 m0, s61, 0x2000
	s_add_u32 s62, s46, 0x40000
	v_lshl_add_u64 v[216:217], s[46:47], 0, v[134:135]
	s_addc_u32 s63, s47, 0
	s_add_i32 s61, s57, s33
	global_load_lds_dwordx4 v[216:217], off
	v_lshl_add_u64 v[218:219], s[62:63], 0, v[138:139]
	s_mov_b32 m0, s61
	v_lshl_add_u64 v[220:221], s[48:49], 0, v[136:137]
	global_load_lds_dwordx4 v[218:219], off
	v_lshl_add_u64 v[218:219], s[62:63], 0, v[134:135]
	s_add_i32 m0, s61, 0x2000
	s_nop 0
	global_load_lds_dwordx4 v[218:219], off
	v_lshl_add_u64 v[218:219], s[48:49], 0, v[140:141]
	s_mov_b32 m0, s50
	s_nop 0
	global_load_lds_dwordx4 v[218:219], off
	s_mov_b32 m0, s51
	s_nop 0
	global_load_lds_dwordx4 v[220:221], off
	s_waitcnt vmcnt(8)
	s_waitcnt lgkmcnt(0)
	s_barrier
; #define PG8_STAGE(bufoff, gbase, voff) do { _Pragma("unroll") for (int _i = 0; _i < 2; ++_i) \
;         __builtin_amdgcn_global_load_lds((const unsigned*)((const char*)(gbase) + (voff)[_i]), (PG8_LAS unsigned*)(lds + (bufoff) + ldsw + _i * 8192), 16, 0, 0); } while (0)
; #define PG8_LDA(dst, b, h) do { _Pragma("unroll") for (int m = 0; m < 4; ++m) _Pragma("unroll") for (int k = 0; k < 2; ++k) dst[m][k] = *(const PG8_LAS bf16x8*)(lds + PG8_SA(b, h) + aoff + m * 2048 + k * 1024); } while (0)
; #define PG8_LDB(dst, b, h) do { _Pragma("unroll") for (int n = 0; n < 2; ++n) _Pragma("unroll") for (int k = 0; k < 2; ++k) dst[n][k] = *(const PG8_LAS bf16x8*)(lds + PG8_SB(b, h) + boff + n * 2048 + k * 1024); } while (0)
; #define PG8_MMA(ai, bj, At, Bt) do { __builtin_amdgcn_s_setprio(1); _Pragma("unroll") for (int m = 0; m < 4; ++m) _Pragma("unroll") for (int n = 0; n < 2; ++n) _Pragma("unroll") for (int k = 0; k < 2; ++k) \
;         acc[ai][bj][m][n] = __builtin_amdgcn_mfma_f32_16x16x32_bf16(Bt[n][k], At[m][k], acc[ai][bj][m][n], 0, 0, 0); __builtin_amdgcn_s_setprio(0); } while (0)
; #define PG8_WAIT_V(n) asm volatile("s_waitcnt vmcnt(" #n ")" ::: "memory")
; #define PG8_WAIT_L(n) asm volatile("s_waitcnt lgkmcnt(" #n ")" ::: "memory")
; #define PG8_BAR __builtin_amdgcn_s_barrier()
; #define PG8_SCHED __builtin_amdgcn_sched_barrier(0)
; template <class Epi, class Sched, bool ALIGN_EPI = false, bool SP2 = false>
; __device__ __forceinline__ void gemm_phase(PG8_LAS unsigned char* lds, const Gemm g, const Sched& S, const Epi& E) {
;     ...
;             PG8_WAIT_V(8); PG8_WAIT_L(0); PG8_BAR; PG8_MMA(0, 0, At, B0); PG8_MMA(0, 1, At, B1); PG8_BAR; PG8_SCHED;
;             PG8_LDA(At, 0, 1); PG8_STAGE(PG8_SB(0, 0), b2, voffB); PG8_STAGE(PG8_SB(0, 1), b2 + hstep, voffB); PG8_STAGE(PG8_SA(0, 0), a2, voffA);
;             PG8_WAIT_V(8); PG8_WAIT_L(0); PG8_BAR; PG8_MMA(1, 0, At, B0); PG8_MMA(1, 1, At, B1); PG8_BAR; PG8_SCHED;
;             PG8_LDB(B0, 1, 0); PG8_LDB(B1, 1, 1); PG8_SCHED; PG8_LDA(At, 1, 0); PG8_STAGE(PG8_SA(0, 1), a2 + hstep, voffA);
;             PG8_WAIT_V(8); PG8_WAIT_L(0); PG8_BAR; PG8_MMA(0, 0, At, B0); PG8_MMA(0, 1, At, B1); PG8_BAR; PG8_SCHED;
	s_setprio 1
	s_waitcnt lgkmcnt(0)
	v_mfma_f32_16x16x32_bf16 v[62:65], v[130:133], v[182:185], v[62:65]
	v_mfma_f32_16x16x32_bf16 v[58:61], v[150:153], v[182:185], v[58:61]
	v_mfma_f32_16x16x32_bf16 v[46:49], v[130:133], v[190:193], v[46:49]
	v_mfma_f32_16x16x32_bf16 v[42:45], v[150:153], v[190:193], v[42:45]
	v_mfma_f32_16x16x32_bf16 v[30:33], v[130:133], v[198:201], v[30:33]
	v_mfma_f32_16x16x32_bf16 v[26:29], v[150:153], v[198:201], v[26:29]
	v_mfma_f32_16x16x32_bf16 v[14:17], v[130:133], v[206:209], v[14:17]
	v_mfma_f32_16x16x32_bf16 v[10:13], v[150:153], v[206:209], v[10:13]
	v_mfma_f32_16x16x32_bf16 v[62:65], v[146:149], v[186:189], v[62:65]
	v_mfma_f32_16x16x32_bf16 v[58:61], v[162:165], v[186:189], v[58:61]
	v_mfma_f32_16x16x32_bf16 v[46:49], v[146:149], v[194:197], v[46:49]
	v_mfma_f32_16x16x32_bf16 v[42:45], v[162:165], v[194:197], v[42:45]
	v_mfma_f32_16x16x32_bf16 v[30:33], v[146:149], v[202:205], v[30:33]
	v_mfma_f32_16x16x32_bf16 v[26:29], v[162:165], v[202:205], v[26:29]
	v_mfma_f32_16x16x32_bf16 v[14:17], v[146:149], v[210:213], v[14:17]
	v_mfma_f32_16x16x32_bf16 v[10:13], v[162:165], v[210:213], v[10:13]
	v_mfma_f32_16x16x32_bf16 v[54:57], v[166:169], v[182:185], v[54:57]
	v_mfma_f32_16x16x32_bf16 v[50:53], v[174:177], v[182:185], v[50:53]
	v_mfma_f32_16x16x32_bf16 v[38:41], v[166:169], v[190:193], v[38:41]
	v_mfma_f32_16x16x32_bf16 v[34:37], v[174:177], v[190:193], v[34:37]
	v_mfma_f32_16x16x32_bf16 v[22:25], v[166:169], v[198:201], v[22:25]
	v_mfma_f32_16x16x32_bf16 v[18:21], v[174:177], v[198:201], v[18:21]
	v_mfma_f32_16x16x32_bf16 v[6:9], v[166:169], v[206:209], v[6:9]
	v_mfma_f32_16x16x32_bf16 v[2:5], v[174:177], v[206:209], v[2:5]
	v_mfma_f32_16x16x32_bf16 v[54:57], v[170:173], v[186:189], v[54:57]
	v_mfma_f32_16x16x32_bf16 v[50:53], v[178:181], v[186:189], v[50:53]
	v_mfma_f32_16x16x32_bf16 v[38:41], v[170:173], v[194:197], v[38:41]
	v_mfma_f32_16x16x32_bf16 v[34:37], v[178:181], v[194:197], v[34:37]
	v_mfma_f32_16x16x32_bf16 v[22:25], v[170:173], v[202:205], v[22:25]
	v_mfma_f32_16x16x32_bf16 v[18:21], v[178:181], v[202:205], v[18:21]
	v_mfma_f32_16x16x32_bf16 v[6:9], v[170:173], v[210:213], v[6:9]
	s_barrier
	v_mfma_f32_16x16x32_bf16 v[2:5], v[178:181], v[210:213], v[2:5]
	s_setprio 0
	s_add_i32 s61, 0, 0x18000
	s_add_i32 s62, 0, 0x1c000
	v_add_u32_e32 v162, s61, v155
	v_add_u32_e32 v178, s62, v155
	ds_read_b128 v[130:133], v162
	ds_read_b128 v[146:149], v162 offset:1024
	ds_read_b128 v[150:153], v162 offset:2048
	ds_read_b128 v[162:165], v162 offset:3072
	ds_read_b128 v[166:169], v178
	ds_read_b128 v[170:173], v178 offset:1024
	ds_read_b128 v[174:177], v178 offset:2048
	ds_read_b128 v[178:181], v178 offset:3072
	s_add_u32 s48, s48, 0x40000
	s_addc_u32 s49, s49, 0
	s_mov_b32 m0, s52
	v_lshl_add_u64 v[222:223], s[48:49], 0, v[140:141]
	ds_read_b128 v[182:185], v161 offset:32768
	ds_read_b128 v[186:189], v161 offset:33792
	ds_read_b128 v[190:193], v161 offset:34816
	ds_read_b128 v[194:197], v161 offset:35840
	ds_read_b128 v[198:201], v161 offset:36864
	ds_read_b128 v[202:205], v161 offset:37888
	ds_read_b128 v[206:209], v161 offset:38912
	ds_read_b128 v[210:213], v161 offset:39936
	global_load_lds_dwordx4 v[222:223], off
	v_lshl_add_u64 v[222:223], s[48:49], 0, v[136:137]
	s_mov_b32 m0, s53
	s_nop 0
	global_load_lds_dwordx4 v[222:223], off
	s_waitcnt vmcnt(8)
	s_waitcnt lgkmcnt(0)
	s_barrier
	s_setprio 1
	s_waitcnt lgkmcnt(0)
	v_mfma_f32_16x16x32_bf16 v[126:129], v[130:133], v[182:185], v[126:129]
	v_mfma_f32_16x16x32_bf16 v[122:125], v[150:153], v[182:185], v[122:125]
	v_mfma_f32_16x16x32_bf16 v[110:113], v[130:133], v[190:193], v[110:113]
	v_mfma_f32_16x16x32_bf16 v[106:109], v[150:153], v[190:193], v[106:109]
	v_mfma_f32_16x16x32_bf16 v[94:97], v[130:133], v[198:201], v[94:97]
	v_mfma_f32_16x16x32_bf16 v[90:93], v[150:153], v[198:201], v[90:93]
	v_mfma_f32_16x16x32_bf16 v[78:81], v[130:133], v[206:209], v[78:81]
	v_mfma_f32_16x16x32_bf16 v[74:77], v[150:153], v[206:209], v[74:77]
	v_mfma_f32_16x16x32_bf16 v[126:129], v[146:149], v[186:189], v[126:129]
	v_mfma_f32_16x16x32_bf16 v[122:125], v[162:165], v[186:189], v[122:125]
	v_mfma_f32_16x16x32_bf16 v[110:113], v[146:149], v[194:197], v[110:113]
	v_mfma_f32_16x16x32_bf16 v[106:109], v[162:165], v[194:197], v[106:109]
	v_mfma_f32_16x16x32_bf16 v[94:97], v[146:149], v[202:205], v[94:97]
	v_mfma_f32_16x16x32_bf16 v[90:93], v[162:165], v[202:205], v[90:93]
	v_mfma_f32_16x16x32_bf16 v[78:81], v[146:149], v[210:213], v[78:81]
	v_mfma_f32_16x16x32_bf16 v[74:77], v[162:165], v[210:213], v[74:77]
	v_mfma_f32_16x16x32_bf16 v[118:121], v[166:169], v[182:185], v[118:121]
	v_mfma_f32_16x16x32_bf16 v[114:117], v[174:177], v[182:185], v[114:117]
	v_mfma_f32_16x16x32_bf16 v[102:105], v[166:169], v[190:193], v[102:105]
	v_mfma_f32_16x16x32_bf16 v[98:101], v[174:177], v[190:193], v[98:101]
	v_mfma_f32_16x16x32_bf16 v[86:89], v[166:169], v[198:201], v[86:89]
	v_mfma_f32_16x16x32_bf16 v[82:85], v[174:177], v[198:201], v[82:85]
	v_mfma_f32_16x16x32_bf16 v[70:73], v[166:169], v[206:209], v[70:73]
	v_mfma_f32_16x16x32_bf16 v[66:69], v[174:177], v[206:209], v[66:69]
	v_mfma_f32_16x16x32_bf16 v[118:121], v[170:173], v[186:189], v[118:121]
	v_mfma_f32_16x16x32_bf16 v[114:117], v[178:181], v[186:189], v[114:117]
	v_mfma_f32_16x16x32_bf16 v[102:105], v[170:173], v[194:197], v[102:105]
	v_mfma_f32_16x16x32_bf16 v[98:101], v[178:181], v[194:197], v[98:101]
	v_mfma_f32_16x16x32_bf16 v[86:89], v[170:173], v[202:205], v[86:89]
	v_mfma_f32_16x16x32_bf16 v[82:85], v[178:181], v[202:205], v[82:85]
	v_mfma_f32_16x16x32_bf16 v[70:73], v[170:173], v[210:213], v[70:73]
	s_barrier
; #define PG8_STAGE(bufoff, gbase, voff) do { _Pragma("unroll") for (int _i = 0; _i < 2; ++_i) \
;         __builtin_amdgcn_global_load_lds((const unsigned*)((const char*)(gbase) + (voff)[_i]), (PG8_LAS unsigned*)(lds + (bufoff) + ldsw + _i * 8192), 16, 0, 0); } while (0)
; #define PG8_LDA(dst, b, h) do { _Pragma("unroll") for (int m = 0; m < 4; ++m) _Pragma("unroll") for (int k = 0; k < 2; ++k) dst[m][k] = *(const PG8_LAS bf16x8*)(lds + PG8_SA(b, h) + aoff + m * 2048 + k * 1024); } while (0)
; #define PG8_MMA(ai, bj, At, Bt) do { __builtin_amdgcn_s_setprio(1); _Pragma("unroll") for (int m = 0; m < 4; ++m) _Pragma("unroll") for (int n = 0; n < 2; ++n) _Pragma("unroll") for (int k = 0; k < 2; ++k) \
;         acc[ai][bj][m][n] = __builtin_amdgcn_mfma_f32_16x16x32_bf16(Bt[n][k], At[m][k], acc[ai][bj][m][n], 0, 0, 0); __builtin_amdgcn_s_setprio(0); } while (0)
; #define PG8_WAIT_V(n) asm volatile("s_waitcnt vmcnt(" #n ")" ::: "memory")
; #define PG8_WAIT_L(n) asm volatile("s_waitcnt lgkmcnt(" #n ")" ::: "memory")
; #define PG8_BAR __builtin_amdgcn_s_barrier()
; #define PG8_SCHED __builtin_amdgcn_sched_barrier(0)
; template <class Epi, class Sched, bool ALIGN_EPI = false, bool SP2 = false>
; __device__ __forceinline__ void gemm_phase(PG8_LAS unsigned char* lds, const Gemm g, const Sched& S, const Epi& E) {
;     ...
;         for (int t = 0; t < nt; t += 2) {
;             const bool last = (t == nt - 2);
;             const char* a1 = cA + (size_t)(t + 1) * kstep;
;             const char* a2 = last ? nA : cA + (size_t)(t + 2) * kstep; const char* b2 = last ? nB : cB + (size_t)(t + 2) * kstep;
;             const char* a3 = a2 + kstep; const char* b3 = b2 + kstep;
;     ...
;             PG8_WAIT_V(8); PG8_WAIT_L(0); PG8_BAR; PG8_MMA(0, 0, At, B0); PG8_MMA(0, 1, At, B1); PG8_BAR; PG8_SCHED;
;             PG8_LDA(At, 1, 1); PG8_STAGE(PG8_SB(1, 0), b3, voffB); PG8_STAGE(PG8_SB(1, 1), b3 + hstep, voffB); PG8_STAGE(PG8_SA(1, 0), a3, voffA);
;             PG8_WAIT_V(8); PG8_WAIT_L(0); PG8_BAR; PG8_MMA(1, 0, At, B0); PG8_MMA(1, 1, At, B1); PG8_BAR; PG8_SCHED;
	v_mfma_f32_16x16x32_bf16 v[66:69], v[178:181], v[210:213], v[66:69]
	s_setprio 0
	s_add_i32 s48, s61, s33
	v_lshl_add_u64 v[214:215], v[214:215], 0, s[12:13]
	s_mov_b32 m0, s48
	ds_read_b128 v[182:185], v161 offset:49152
	ds_read_b128 v[186:189], v161 offset:50176
	ds_read_b128 v[190:193], v161 offset:51200
	ds_read_b128 v[194:197], v161 offset:52224
	ds_read_b128 v[198:201], v161 offset:53248
	ds_read_b128 v[202:205], v161 offset:54272
	ds_read_b128 v[206:209], v161 offset:55296
	ds_read_b128 v[210:213], v161 offset:56320
	global_load_lds_dwordx4 v[214:215], off
	s_add_i32 m0, s48, 0x2000
	s_add_u32 s46, s46, 0x40080
	v_lshl_add_u64 v[214:215], v[216:217], 0, s[12:13]
	s_addc_u32 s47, s47, 0
	s_add_i32 s48, s62, s33
	global_load_lds_dwordx4 v[214:215], off
	v_lshl_add_u64 v[214:215], s[46:47], 0, v[138:139]
	s_mov_b32 m0, s48
	s_nop 0
	global_load_lds_dwordx4 v[214:215], off
	v_lshl_add_u64 v[214:215], s[46:47], 0, v[134:135]
	s_add_i32 m0, s48, 0x2000
	s_nop 0
	global_load_lds_dwordx4 v[214:215], off
	v_lshl_add_u64 v[214:215], v[218:219], 0, s[12:13]
	s_mov_b32 m0, s54
	s_nop 0
	global_load_lds_dwordx4 v[214:215], off
	v_lshl_add_u64 v[214:215], v[220:221], 0, s[12:13]
	s_mov_b32 m0, s55
	s_nop 0
	global_load_lds_dwordx4 v[214:215], off
	s_waitcnt vmcnt(8)
	s_waitcnt lgkmcnt(0)
	s_barrier
	s_setprio 1
	s_waitcnt lgkmcnt(0)
	v_mfma_f32_16x16x32_bf16 v[62:65], v[130:133], v[182:185], v[62:65]
	v_mfma_f32_16x16x32_bf16 v[58:61], v[150:153], v[182:185], v[58:61]
	v_mfma_f32_16x16x32_bf16 v[46:49], v[130:133], v[190:193], v[46:49]
	v_mfma_f32_16x16x32_bf16 v[42:45], v[150:153], v[190:193], v[42:45]
	v_mfma_f32_16x16x32_bf16 v[30:33], v[130:133], v[198:201], v[30:33]
	v_mfma_f32_16x16x32_bf16 v[26:29], v[150:153], v[198:201], v[26:29]
	v_mfma_f32_16x16x32_bf16 v[14:17], v[130:133], v[206:209], v[14:17]
	v_mfma_f32_16x16x32_bf16 v[10:13], v[150:153], v[206:209], v[10:13]
	v_mfma_f32_16x16x32_bf16 v[62:65], v[146:149], v[186:189], v[62:65]
	v_mfma_f32_16x16x32_bf16 v[58:61], v[162:165], v[186:189], v[58:61]
	v_mfma_f32_16x16x32_bf16 v[46:49], v[146:149], v[194:197], v[46:49]
	v_mfma_f32_16x16x32_bf16 v[42:45], v[162:165], v[194:197], v[42:45]
	v_mfma_f32_16x16x32_bf16 v[30:33], v[146:149], v[202:205], v[30:33]
	v_mfma_f32_16x16x32_bf16 v[26:29], v[162:165], v[202:205], v[26:29]
	v_mfma_f32_16x16x32_bf16 v[14:17], v[146:149], v[210:213], v[14:17]
	v_mfma_f32_16x16x32_bf16 v[10:13], v[162:165], v[210:213], v[10:13]
	v_mfma_f32_16x16x32_bf16 v[54:57], v[166:169], v[182:185], v[54:57]
	v_mfma_f32_16x16x32_bf16 v[50:53], v[174:177], v[182:185], v[50:53]
	v_mfma_f32_16x16x32_bf16 v[38:41], v[166:169], v[190:193], v[38:41]
	v_mfma_f32_16x16x32_bf16 v[34:37], v[174:177], v[190:193], v[34:37]
	v_mfma_f32_16x16x32_bf16 v[22:25], v[166:169], v[198:201], v[22:25]
	v_mfma_f32_16x16x32_bf16 v[18:21], v[174:177], v[198:201], v[18:21]
	v_mfma_f32_16x16x32_bf16 v[6:9], v[166:169], v[206:209], v[6:9]
	v_mfma_f32_16x16x32_bf16 v[2:5], v[174:177], v[206:209], v[2:5]
	v_mfma_f32_16x16x32_bf16 v[54:57], v[170:173], v[186:189], v[54:57]
	v_mfma_f32_16x16x32_bf16 v[50:53], v[178:181], v[186:189], v[50:53]
	v_mfma_f32_16x16x32_bf16 v[38:41], v[170:173], v[194:197], v[38:41]
	v_mfma_f32_16x16x32_bf16 v[34:37], v[178:181], v[194:197], v[34:37]
	v_mfma_f32_16x16x32_bf16 v[22:25], v[170:173], v[202:205], v[22:25]
	v_mfma_f32_16x16x32_bf16 v[18:21], v[178:181], v[202:205], v[18:21]
	v_mfma_f32_16x16x32_bf16 v[6:9], v[170:173], v[210:213], v[6:9]
	s_barrier
	v_mfma_f32_16x16x32_bf16 v[2:5], v[178:181], v[210:213], v[2:5]
	s_setprio 0
	s_add_i32 s60, s60, 2
	s_add_u32 s44, s44, 0x100
	s_addc_u32 s45, s45, 0
	s_add_u32 s58, s58, 0x100
	s_addc_u32 s59, s59, 0
	s_cmp_gt_u32 s60, 13
	s_cbranch_scc0 .LBB0_884
	s_and_b64 vcc, exec, s[14:15]
	s_cbranch_vccz .LBB0_887
	s_barrier

; #define PG8_STAGE(bufoff, gbase, voff) do { _Pragma("unroll") for (int _i = 0; _i < 2; ++_i) \
;         __builtin_amdgcn_global_load_lds((const unsigned*)((const char*)(gbase) + (voff)[_i]), (PG8_LAS unsigned*)(lds + (bufoff) + ldsw + _i * 8192), 16, 0, 0); } while (0)
; #define PG8_LDA(dst, b, h) do { _Pragma("unroll") for (int m = 0; m < 4; ++m) _Pragma("unroll") for (int k = 0; k < 2; ++k) dst[m][k] = *(const PG8_LAS bf16x8*)(lds + PG8_SA(b, h) + aoff + m * 2048 + k * 1024); } while (0)
; #define PG8_LDB(dst, b, h) do { _Pragma("unroll") for (int n = 0; n < 2; ++n) _Pragma("unroll") for (int k = 0; k < 2; ++k) dst[n][k] = *(const PG8_LAS bf16x8*)(lds + PG8_SB(b, h) + boff + n * 2048 + k * 1024); } while (0)
; #define PG8_MMA(ai, bj, At, Bt) do { __builtin_amdgcn_s_setprio(1); _Pragma("unroll") for (int m = 0; m < 4; ++m) _Pragma("unroll") for (int n = 0; n < 2; ++n) _Pragma("unroll") for (int k = 0; k < 2; ++k) \
;         acc[ai][bj][m][n] = __builtin_amdgcn_mfma_f32_16x16x32_bf16(Bt[n][k], At[m][k], acc[ai][bj][m][n], 0, 0, 0); __builtin_amdgcn_s_setprio(0); } while (0)
; #define PG8_WAIT_V(n) asm volatile("s_waitcnt vmcnt(" #n ")" ::: "memory")
; #define PG8_WAIT_L(n) asm volatile("s_waitcnt lgkmcnt(" #n ")" ::: "memory")
; #define PG8_BAR __builtin_amdgcn_s_barrier()
; template <class Epi, class Sched, bool ALIGN_EPI = false, bool SP2 = false>
; __device__ __forceinline__ void gemm_phase(PG8_LAS unsigned char* lds, const Gemm g, const Sched& S, const Epi& E) {
;     ...
;             const char* a1 = cA + (size_t)(t + 1) * kstep;
;             const char* a2 = last ? nA : cA + (size_t)(t + 2) * kstep; const char* b2 = last ? nB : cB + (size_t)(t + 2) * kstep;
;             const char* a3 = a2 + kstep; const char* b3 = b2 + kstep;
;             if (last && has_next) S.a_ready(nxt);
;             if constexpr (SP2) {
;             PG8_LDB(B0, 0, 0); PG8_LDB(B1, 0, 1); PG8_SCHED; PG8_LDA(At, 0, 0); PG8_STAGE(PG8_SA(1, 1), a1 + hstep, voffA);
;             PG8_WAIT_V(8); PG8_WAIT_L(0); PG8_BAR; PG8_MMA(0, 0, At, B0); PG8_MMA(0, 1, At, B1); PG8_BAR; PG8_SCHED;
;             PG8_LDA(At, 0, 1); PG8_STAGE(PG8_SB(0, 0), b2, voffB); PG8_STAGE(PG8_SB(0, 1), b2 + hstep, voffB); PG8_STAGE(PG8_SA(0, 0), a2, voffA);
;             PG8_WAIT_V(8); PG8_WAIT_L(0); PG8_BAR; PG8_MMA(1, 0, At, B0); PG8_MMA(1, 1, At, B1); PG8_BAR; PG8_SCHED;
.LBB0_968:
	v_add_u32_e32 v162, s45, v148
	v_add_u32_e32 v178, s46, v148
	s_add_u32 s22, s8, s20
	ds_read_b128 v[150:153], v162
	ds_read_b128 v[154:157], v162 offset:1024
	ds_read_b128 v[158:161], v162 offset:2048
	ds_read_b128 v[162:165], v162 offset:3072
	ds_read_b128 v[166:169], v178
	ds_read_b128 v[170:173], v178 offset:1024
	ds_read_b128 v[174:177], v178 offset:2048
	ds_read_b128 v[178:181], v178 offset:3072
	s_addc_u32 s23, s9, s21
	s_add_u32 s22, s22, 0x100
	s_addc_u32 s23, s23, 0
	s_add_u32 s51, s48, s20
	s_addc_u32 s52, s49, s21
	s_cmpk_eq_i32 s20, 0x700
	s_cselect_b32 s25, s19, s23
	s_cselect_b32 s24, s18, s22
	s_cselect_b32 s23, s13, s52
	s_cselect_b32 s22, s15, s51
	v_lshl_add_u64 v[214:215], v[142:143], 0, s[20:21]
	s_add_i32 m0, s5, 0xc000
	ds_read_b128 v[182:185], v149
	ds_read_b128 v[186:189], v149 offset:1024
	ds_read_b128 v[190:193], v149 offset:2048
	ds_read_b128 v[194:197], v149 offset:3072
	ds_read_b128 v[198:201], v149 offset:4096
	ds_read_b128 v[202:205], v149 offset:5120
	ds_read_b128 v[206:209], v149 offset:6144
	ds_read_b128 v[210:213], v149 offset:7168
	global_load_lds_dwordx4 v[214:215], off
	v_lshl_add_u64 v[214:215], v[144:145], 0, s[20:21]
	s_add_i32 m0, s5, 0xe000
	s_nop 0
	global_load_lds_dwordx4 v[214:215], off
	s_waitcnt vmcnt(8)
	s_waitcnt lgkmcnt(0)
	s_barrier
	s_setprio 1
	s_waitcnt lgkmcnt(0)
	v_mfma_f32_16x16x32_bf16 v[126:129], v[150:153], v[182:185], v[126:129]
	v_mfma_f32_16x16x32_bf16 v[122:125], v[158:161], v[182:185], v[122:125]
	v_mfma_f32_16x16x32_bf16 v[114:117], v[150:153], v[190:193], v[114:117]
	v_mfma_f32_16x16x32_bf16 v[106:109], v[158:161], v[190:193], v[106:109]
	v_mfma_f32_16x16x32_bf16 v[98:101], v[150:153], v[198:201], v[98:101]
	v_mfma_f32_16x16x32_bf16 v[90:93], v[158:161], v[198:201], v[90:93]
	v_mfma_f32_16x16x32_bf16 v[82:85], v[150:153], v[206:209], v[82:85]
	v_mfma_f32_16x16x32_bf16 v[74:77], v[158:161], v[206:209], v[74:77]
	v_mfma_f32_16x16x32_bf16 v[126:129], v[154:157], v[186:189], v[126:129]
	v_mfma_f32_16x16x32_bf16 v[122:125], v[162:165], v[186:189], v[122:125]
	v_mfma_f32_16x16x32_bf16 v[114:117], v[154:157], v[194:197], v[114:117]
	v_mfma_f32_16x16x32_bf16 v[106:109], v[162:165], v[194:197], v[106:109]
	v_mfma_f32_16x16x32_bf16 v[98:101], v[154:157], v[202:205], v[98:101]
	v_mfma_f32_16x16x32_bf16 v[90:93], v[162:165], v[202:205], v[90:93]
	v_mfma_f32_16x16x32_bf16 v[82:85], v[154:157], v[210:213], v[82:85]
	v_mfma_f32_16x16x32_bf16 v[74:77], v[162:165], v[210:213], v[74:77]
	v_mfma_f32_16x16x32_bf16 v[118:121], v[166:169], v[182:185], v[118:121]
	v_mfma_f32_16x16x32_bf16 v[110:113], v[174:177], v[182:185], v[110:113]
	v_mfma_f32_16x16x32_bf16 v[102:105], v[166:169], v[190:193], v[102:105]
	v_mfma_f32_16x16x32_bf16 v[94:97], v[174:177], v[190:193], v[94:97]
	v_mfma_f32_16x16x32_bf16 v[86:89], v[166:169], v[198:201], v[86:89]
	v_mfma_f32_16x16x32_bf16 v[78:81], v[174:177], v[198:201], v[78:81]
	v_mfma_f32_16x16x32_bf16 v[70:73], v[166:169], v[206:209], v[70:73]
	v_mfma_f32_16x16x32_bf16 v[66:69], v[174:177], v[206:209], v[66:69]
	v_mfma_f32_16x16x32_bf16 v[118:121], v[170:173], v[186:189], v[118:121]
	v_mfma_f32_16x16x32_bf16 v[110:113], v[178:181], v[186:189], v[110:113]
	v_mfma_f32_16x16x32_bf16 v[102:105], v[170:173], v[194:197], v[102:105]
	v_mfma_f32_16x16x32_bf16 v[94:97], v[178:181], v[194:197], v[94:97]
	v_mfma_f32_16x16x32_bf16 v[86:89], v[170:173], v[202:205], v[86:89]
	v_mfma_f32_16x16x32_bf16 v[78:81], v[178:181], v[202:205], v[78:81]
	v_mfma_f32_16x16x32_bf16 v[70:73], v[170:173], v[210:213], v[70:73]
	s_barrier
	v_mfma_f32_16x16x32_bf16 v[66:69], v[178:181], v[210:213], v[66:69]
	s_setprio 0
	s_add_i32 s51, s45, s38
	v_lshl_add_u64 v[214:215], s[22:23], 0, v[130:131]
	s_mov_b32 m0, s51
	ds_read_b128 v[182:185], v149 offset:16384
	ds_read_b128 v[186:189], v149 offset:17408
	ds_read_b128 v[190:193], v149 offset:18432
	ds_read_b128 v[194:197], v149 offset:19456
	ds_read_b128 v[198:201], v149 offset:20480
	ds_read_b128 v[202:205], v149 offset:21504
	ds_read_b128 v[206:209], v149 offset:22528
	ds_read_b128 v[210:213], v149 offset:23552
	global_load_lds_dwordx4 v[214:215], off
	s_add_i32 m0, s51, 0x2000
	s_add_u32 s52, s22, 0x40000
	v_lshl_add_u64 v[216:217], s[22:23], 0, v[132:133]
	s_addc_u32 s53, s23, 0
	s_add_i32 s51, s46, s38
	global_load_lds_dwordx4 v[216:217], off
	v_lshl_add_u64 v[218:219], s[52:53], 0, v[130:131]
	s_mov_b32 m0, s51
	v_lshl_add_u64 v[220:221], s[24:25], 0, v[132:133]
	global_load_lds_dwordx4 v[218:219], off
	v_lshl_add_u64 v[218:219], s[52:53], 0, v[132:133]
	s_add_i32 m0, s51, 0x2000
	s_nop 0
	global_load_lds_dwordx4 v[218:219], off
	v_lshl_add_u64 v[218:219], s[24:25], 0, v[130:131]
	s_mov_b32 m0, s5
	s_nop 0
	global_load_lds_dwordx4 v[218:219], off
	s_mov_b32 m0, s39
	s_nop 0
	global_load_lds_dwordx4 v[220:221], off
	s_waitcnt vmcnt(8)
	s_waitcnt lgkmcnt(0)
	s_barrier
; #define PG8_STAGE(bufoff, gbase, voff) do { _Pragma("unroll") for (int _i = 0; _i < 2; ++_i) \
;         __builtin_amdgcn_global_load_lds((const unsigned*)((const char*)(gbase) + (voff)[_i]), (PG8_LAS unsigned*)(lds + (bufoff) + ldsw + _i * 8192), 16, 0, 0); } while (0)
; #define PG8_LDA(dst, b, h) do { _Pragma("unroll") for (int m = 0; m < 4; ++m) _Pragma("unroll") for (int k = 0; k < 2; ++k) dst[m][k] = *(const PG8_LAS bf16x8*)(lds + PG8_SA(b, h) + aoff + m * 2048 + k * 1024); } while (0)
; #define PG8_LDB(dst, b, h) do { _Pragma("unroll") for (int n = 0; n < 2; ++n) _Pragma("unroll") for (int k = 0; k < 2; ++k) dst[n][k] = *(const PG8_LAS bf16x8*)(lds + PG8_SB(b, h) + boff + n * 2048 + k * 1024); } while (0)
; #define PG8_MMA(ai, bj, At, Bt) do { __builtin_amdgcn_s_setprio(1); _Pragma("unroll") for (int m = 0; m < 4; ++m) _Pragma("unroll") for (int n = 0; n < 2; ++n) _Pragma("unroll") for (int k = 0; k < 2; ++k) \
;         acc[ai][bj][m][n] = __builtin_amdgcn_mfma_f32_16x16x32_bf16(Bt[n][k], At[m][k], acc[ai][bj][m][n], 0, 0, 0); __builtin_amdgcn_s_setprio(0); } while (0)
; #define PG8_WAIT_V(n) asm volatile("s_waitcnt vmcnt(" #n ")" ::: "memory")
; #define PG8_WAIT_L(n) asm volatile("s_waitcnt lgkmcnt(" #n ")" ::: "memory")
; #define PG8_BAR __builtin_amdgcn_s_barrier()
; #define PG8_SCHED __builtin_amdgcn_sched_barrier(0)
; template <class Epi, class Sched, bool ALIGN_EPI = false, bool SP2 = false>
; __device__ __forceinline__ void gemm_phase(PG8_LAS unsigned char* lds, const Gemm g, const Sched& S, const Epi& E) {
;     ...
;             PG8_WAIT_V(8); PG8_WAIT_L(0); PG8_BAR; PG8_MMA(0, 0, At, B0); PG8_MMA(0, 1, At, B1); PG8_BAR; PG8_SCHED;
;             PG8_LDA(At, 0, 1); PG8_STAGE(PG8_SB(0, 0), b2, voffB); PG8_STAGE(PG8_SB(0, 1), b2 + hstep, voffB); PG8_STAGE(PG8_SA(0, 0), a2, voffA);
;             PG8_WAIT_V(8); PG8_WAIT_L(0); PG8_BAR; PG8_MMA(1, 0, At, B0); PG8_MMA(1, 1, At, B1); PG8_BAR; PG8_SCHED;
;             PG8_LDB(B0, 1, 0); PG8_LDB(B1, 1, 1); PG8_SCHED; PG8_LDA(At, 1, 0); PG8_STAGE(PG8_SA(0, 1), a2 + hstep, voffA);
;             PG8_WAIT_V(8); PG8_WAIT_L(0); PG8_BAR; PG8_MMA(0, 0, At, B0); PG8_MMA(0, 1, At, B1); PG8_BAR; PG8_SCHED;
	s_setprio 1
	s_waitcnt lgkmcnt(0)
	v_mfma_f32_16x16x32_bf16 v[62:65], v[150:153], v[182:185], v[62:65]
	v_mfma_f32_16x16x32_bf16 v[58:61], v[158:161], v[182:185], v[58:61]
	v_mfma_f32_16x16x32_bf16 v[50:53], v[150:153], v[190:193], v[50:53]
	v_mfma_f32_16x16x32_bf16 v[42:45], v[158:161], v[190:193], v[42:45]
	v_mfma_f32_16x16x32_bf16 v[34:37], v[150:153], v[198:201], v[34:37]
	v_mfma_f32_16x16x32_bf16 v[26:29], v[158:161], v[198:201], v[26:29]
	v_mfma_f32_16x16x32_bf16 v[18:21], v[150:153], v[206:209], v[18:21]
	v_mfma_f32_16x16x32_bf16 v[10:13], v[158:161], v[206:209], v[10:13]
	v_mfma_f32_16x16x32_bf16 v[62:65], v[154:157], v[186:189], v[62:65]
	v_mfma_f32_16x16x32_bf16 v[58:61], v[162:165], v[186:189], v[58:61]
	v_mfma_f32_16x16x32_bf16 v[50:53], v[154:157], v[194:197], v[50:53]
	v_mfma_f32_16x16x32_bf16 v[42:45], v[162:165], v[194:197], v[42:45]
	v_mfma_f32_16x16x32_bf16 v[34:37], v[154:157], v[202:205], v[34:37]
	v_mfma_f32_16x16x32_bf16 v[26:29], v[162:165], v[202:205], v[26:29]
	v_mfma_f32_16x16x32_bf16 v[18:21], v[154:157], v[210:213], v[18:21]
	v_mfma_f32_16x16x32_bf16 v[10:13], v[162:165], v[210:213], v[10:13]
	v_mfma_f32_16x16x32_bf16 v[54:57], v[166:169], v[182:185], v[54:57]
	v_mfma_f32_16x16x32_bf16 v[46:49], v[174:177], v[182:185], v[46:49]
	v_mfma_f32_16x16x32_bf16 v[38:41], v[166:169], v[190:193], v[38:41]
	v_mfma_f32_16x16x32_bf16 v[30:33], v[174:177], v[190:193], v[30:33]
	v_mfma_f32_16x16x32_bf16 v[22:25], v[166:169], v[198:201], v[22:25]
	v_mfma_f32_16x16x32_bf16 v[14:17], v[174:177], v[198:201], v[14:17]
	v_mfma_f32_16x16x32_bf16 v[6:9], v[166:169], v[206:209], v[6:9]
	v_mfma_f32_16x16x32_bf16 v[2:5], v[174:177], v[206:209], v[2:5]
	v_mfma_f32_16x16x32_bf16 v[54:57], v[170:173], v[186:189], v[54:57]
	v_mfma_f32_16x16x32_bf16 v[46:49], v[178:181], v[186:189], v[46:49]
	v_mfma_f32_16x16x32_bf16 v[38:41], v[170:173], v[194:197], v[38:41]
	v_mfma_f32_16x16x32_bf16 v[30:33], v[178:181], v[194:197], v[30:33]
	v_mfma_f32_16x16x32_bf16 v[22:25], v[170:173], v[202:205], v[22:25]
	v_mfma_f32_16x16x32_bf16 v[14:17], v[178:181], v[202:205], v[14:17]
	v_mfma_f32_16x16x32_bf16 v[6:9], v[170:173], v[210:213], v[6:9]
	s_barrier
	v_mfma_f32_16x16x32_bf16 v[2:5], v[178:181], v[210:213], v[2:5]
	s_setprio 0
	s_add_i32 s51, 0, 0x18000
	s_add_i32 s52, 0, 0x1c000
	v_add_u32_e32 v162, s51, v148
	v_add_u32_e32 v178, s52, v148
	ds_read_b128 v[150:153], v162
	ds_read_b128 v[154:157], v162 offset:1024
	ds_read_b128 v[158:161], v162 offset:2048
	ds_read_b128 v[162:165], v162 offset:3072
	ds_read_b128 v[166:169], v178
	ds_read_b128 v[170:173], v178 offset:1024
	ds_read_b128 v[174:177], v178 offset:2048
	ds_read_b128 v[178:181], v178 offset:3072
	s_add_u32 s24, s24, 0x40000
	s_addc_u32 s25, s25, 0
	s_mov_b32 m0, s40
	v_lshl_add_u64 v[222:223], s[24:25], 0, v[130:131]
	ds_read_b128 v[182:185], v149 offset:32768
	ds_read_b128 v[186:189], v149 offset:33792
	ds_read_b128 v[190:193], v149 offset:34816
	ds_read_b128 v[194:197], v149 offset:35840
	ds_read_b128 v[198:201], v149 offset:36864
	ds_read_b128 v[202:205], v149 offset:37888
	ds_read_b128 v[206:209], v149 offset:38912
	ds_read_b128 v[210:213], v149 offset:39936
	global_load_lds_dwordx4 v[222:223], off
	v_lshl_add_u64 v[222:223], s[24:25], 0, v[132:133]
	s_mov_b32 m0, s41
	s_nop 0
	global_load_lds_dwordx4 v[222:223], off
	s_waitcnt vmcnt(8)
	s_waitcnt lgkmcnt(0)
	s_barrier
	s_setprio 1
	s_waitcnt lgkmcnt(0)
	v_mfma_f32_16x16x32_bf16 v[126:129], v[150:153], v[182:185], v[126:129]
	v_mfma_f32_16x16x32_bf16 v[122:125], v[158:161], v[182:185], v[122:125]
	v_mfma_f32_16x16x32_bf16 v[114:117], v[150:153], v[190:193], v[114:117]
	v_mfma_f32_16x16x32_bf16 v[106:109], v[158:161], v[190:193], v[106:109]
	v_mfma_f32_16x16x32_bf16 v[98:101], v[150:153], v[198:201], v[98:101]
	v_mfma_f32_16x16x32_bf16 v[90:93], v[158:161], v[198:201], v[90:93]
	v_mfma_f32_16x16x32_bf16 v[82:85], v[150:153], v[206:209], v[82:85]
	v_mfma_f32_16x16x32_bf16 v[74:77], v[158:161], v[206:209], v[74:77]
	v_mfma_f32_16x16x32_bf16 v[126:129], v[154:157], v[186:189], v[126:129]
	v_mfma_f32_16x16x32_bf16 v[122:125], v[162:165], v[186:189], v[122:125]
	v_mfma_f32_16x16x32_bf16 v[114:117], v[154:157], v[194:197], v[114:117]
	v_mfma_f32_16x16x32_bf16 v[106:109], v[162:165], v[194:197], v[106:109]
	v_mfma_f32_16x16x32_bf16 v[98:101], v[154:157], v[202:205], v[98:101]
	v_mfma_f32_16x16x32_bf16 v[90:93], v[162:165], v[202:205], v[90:93]
	v_mfma_f32_16x16x32_bf16 v[82:85], v[154:157], v[210:213], v[82:85]
	v_mfma_f32_16x16x32_bf16 v[74:77], v[162:165], v[210:213], v[74:77]
	v_mfma_f32_16x16x32_bf16 v[118:121], v[166:169], v[182:185], v[118:121]
	v_mfma_f32_16x16x32_bf16 v[110:113], v[174:177], v[182:185], v[110:113]
	v_mfma_f32_16x16x32_bf16 v[102:105], v[166:169], v[190:193], v[102:105]
	v_mfma_f32_16x16x32_bf16 v[94:97], v[174:177], v[190:193], v[94:97]
	v_mfma_f32_16x16x32_bf16 v[86:89], v[166:169], v[198:201], v[86:89]
	v_mfma_f32_16x16x32_bf16 v[78:81], v[174:177], v[198:201], v[78:81]
	v_mfma_f32_16x16x32_bf16 v[70:73], v[166:169], v[206:209], v[70:73]
	v_mfma_f32_16x16x32_bf16 v[66:69], v[174:177], v[206:209], v[66:69]
	v_mfma_f32_16x16x32_bf16 v[118:121], v[170:173], v[186:189], v[118:121]
	v_mfma_f32_16x16x32_bf16 v[110:113], v[178:181], v[186:189], v[110:113]
	v_mfma_f32_16x16x32_bf16 v[102:105], v[170:173], v[194:197], v[102:105]
	v_mfma_f32_16x16x32_bf16 v[94:97], v[178:181], v[194:197], v[94:97]
	v_mfma_f32_16x16x32_bf16 v[86:89], v[170:173], v[202:205], v[86:89]
	v_mfma_f32_16x16x32_bf16 v[78:81], v[178:181], v[202:205], v[78:81]
	v_mfma_f32_16x16x32_bf16 v[70:73], v[170:173], v[210:213], v[70:73]
	s_barrier
; #define PG8_STAGE(bufoff, gbase, voff) do { _Pragma("unroll") for (int _i = 0; _i < 2; ++_i) \
;         __builtin_amdgcn_global_load_lds((const unsigned*)((const char*)(gbase) + (voff)[_i]), (PG8_LAS unsigned*)(lds + (bufoff) + ldsw + _i * 8192), 16, 0, 0); } while (0)
; #define PG8_LDA(dst, b, h) do { _Pragma("unroll") for (int m = 0; m < 4; ++m) _Pragma("unroll") for (int k = 0; k < 2; ++k) dst[m][k] = *(const PG8_LAS bf16x8*)(lds + PG8_SA(b, h) + aoff + m * 2048 + k * 1024); } while (0)
; #define PG8_MMA(ai, bj, At, Bt) do { __builtin_amdgcn_s_setprio(1); _Pragma("unroll") for (int m = 0; m < 4; ++m) _Pragma("unroll") for (int n = 0; n < 2; ++n) _Pragma("unroll") for (int k = 0; k < 2; ++k) \
;         acc[ai][bj][m][n] = __builtin_amdgcn_mfma_f32_16x16x32_bf16(Bt[n][k], At[m][k], acc[ai][bj][m][n], 0, 0, 0); __builtin_amdgcn_s_setprio(0); } while (0)
; #define PG8_WAIT_V(n) asm volatile("s_waitcnt vmcnt(" #n ")" ::: "memory")
; #define PG8_WAIT_L(n) asm volatile("s_waitcnt lgkmcnt(" #n ")" ::: "memory")
; #define PG8_BAR __builtin_amdgcn_s_barrier()
; #define PG8_SCHED __builtin_amdgcn_sched_barrier(0)
; template <class Epi, class Sched, bool ALIGN_EPI = false, bool SP2 = false>
; __device__ __forceinline__ void gemm_phase(PG8_LAS unsigned char* lds, const Gemm g, const Sched& S, const Epi& E) {
;     ...
;             PG8_WAIT_V(8); PG8_WAIT_L(0); PG8_BAR; PG8_MMA(0, 0, At, B0); PG8_MMA(0, 1, At, B1); PG8_BAR; PG8_SCHED;
;             PG8_LDA(At, 1, 1); PG8_STAGE(PG8_SB(1, 0), b3, voffB); PG8_STAGE(PG8_SB(1, 1), b3 + hstep, voffB); PG8_STAGE(PG8_SA(1, 0), a3, voffA);
;             PG8_WAIT_V(8); PG8_WAIT_L(0); PG8_BAR; PG8_MMA(1, 0, At, B0); PG8_MMA(1, 1, At, B1); PG8_BAR; PG8_SCHED;
;     ...
;         if (!has_next) break;
; #pragma unroll
;         for (int a = 0; a < 2; ++a)
; #pragma unroll
;             for (int b = 0; b < 2; ++b)
; #pragma unroll
;                 for (int m = 0; m < 4; ++m)
; #pragma unroll
;                     for (int n = 0; n < 2; ++n) acc[a][b][m][n] = (f32x4){0.f, 0.f, 0.f, 0.f};
;         cur = nxt; cA = nA; cB = nB; ++ui;
	v_mfma_f32_16x16x32_bf16 v[66:69], v[178:181], v[210:213], v[66:69]
	s_setprio 0
	s_add_i32 s24, s51, s38
	v_lshl_add_u64 v[214:215], v[214:215], 0, s[10:11]
	s_mov_b32 m0, s24
	ds_read_b128 v[182:185], v149 offset:49152
	ds_read_b128 v[186:189], v149 offset:50176
	ds_read_b128 v[190:193], v149 offset:51200
	ds_read_b128 v[194:197], v149 offset:52224
	ds_read_b128 v[198:201], v149 offset:53248
	ds_read_b128 v[202:205], v149 offset:54272
	ds_read_b128 v[206:209], v149 offset:55296
	ds_read_b128 v[210:213], v149 offset:56320
	global_load_lds_dwordx4 v[214:215], off
	s_add_i32 m0, s24, 0x2000
	s_add_u32 s22, s22, 0x40080
	v_lshl_add_u64 v[214:215], v[216:217], 0, s[10:11]
	s_addc_u32 s23, s23, 0
	s_add_i32 s24, s52, s38
	global_load_lds_dwordx4 v[214:215], off
	v_lshl_add_u64 v[214:215], s[22:23], 0, v[130:131]
	s_mov_b32 m0, s24
	s_nop 0
	global_load_lds_dwordx4 v[214:215], off
	v_lshl_add_u64 v[214:215], s[22:23], 0, v[132:133]
	s_add_i32 m0, s24, 0x2000
	s_nop 0
	global_load_lds_dwordx4 v[214:215], off
	v_lshl_add_u64 v[214:215], v[218:219], 0, s[10:11]
	s_mov_b32 m0, s42
	s_nop 0
	global_load_lds_dwordx4 v[214:215], off
	v_lshl_add_u64 v[214:215], v[220:221], 0, s[10:11]
	s_mov_b32 m0, s43
	s_nop 0
	global_load_lds_dwordx4 v[214:215], off
	s_waitcnt vmcnt(8)
	s_waitcnt lgkmcnt(0)
	s_barrier
	s_setprio 1
	s_waitcnt lgkmcnt(0)
	v_mfma_f32_16x16x32_bf16 v[62:65], v[150:153], v[182:185], v[62:65]
	v_mfma_f32_16x16x32_bf16 v[58:61], v[158:161], v[182:185], v[58:61]
	v_mfma_f32_16x16x32_bf16 v[50:53], v[150:153], v[190:193], v[50:53]
	v_mfma_f32_16x16x32_bf16 v[42:45], v[158:161], v[190:193], v[42:45]
	v_mfma_f32_16x16x32_bf16 v[34:37], v[150:153], v[198:201], v[34:37]
	v_mfma_f32_16x16x32_bf16 v[26:29], v[158:161], v[198:201], v[26:29]
	v_mfma_f32_16x16x32_bf16 v[18:21], v[150:153], v[206:209], v[18:21]
	v_mfma_f32_16x16x32_bf16 v[10:13], v[158:161], v[206:209], v[10:13]
	v_mfma_f32_16x16x32_bf16 v[62:65], v[154:157], v[186:189], v[62:65]
	v_mfma_f32_16x16x32_bf16 v[58:61], v[162:165], v[186:189], v[58:61]
	v_mfma_f32_16x16x32_bf16 v[50:53], v[154:157], v[194:197], v[50:53]
	v_mfma_f32_16x16x32_bf16 v[42:45], v[162:165], v[194:197], v[42:45]
	v_mfma_f32_16x16x32_bf16 v[34:37], v[154:157], v[202:205], v[34:37]
	v_mfma_f32_16x16x32_bf16 v[26:29], v[162:165], v[202:205], v[26:29]
	v_mfma_f32_16x16x32_bf16 v[18:21], v[154:157], v[210:213], v[18:21]
	v_mfma_f32_16x16x32_bf16 v[10:13], v[162:165], v[210:213], v[10:13]
	v_mfma_f32_16x16x32_bf16 v[54:57], v[166:169], v[182:185], v[54:57]
	v_mfma_f32_16x16x32_bf16 v[46:49], v[174:177], v[182:185], v[46:49]
	v_mfma_f32_16x16x32_bf16 v[38:41], v[166:169], v[190:193], v[38:41]
	v_mfma_f32_16x16x32_bf16 v[30:33], v[174:177], v[190:193], v[30:33]
	v_mfma_f32_16x16x32_bf16 v[22:25], v[166:169], v[198:201], v[22:25]
	v_mfma_f32_16x16x32_bf16 v[14:17], v[174:177], v[198:201], v[14:17]
	v_mfma_f32_16x16x32_bf16 v[6:9], v[166:169], v[206:209], v[6:9]
	v_mfma_f32_16x16x32_bf16 v[2:5], v[174:177], v[206:209], v[2:5]
	v_mfma_f32_16x16x32_bf16 v[54:57], v[170:173], v[186:189], v[54:57]
	v_mfma_f32_16x16x32_bf16 v[46:49], v[178:181], v[186:189], v[46:49]
	v_mfma_f32_16x16x32_bf16 v[38:41], v[170:173], v[194:197], v[38:41]
	v_mfma_f32_16x16x32_bf16 v[30:33], v[178:181], v[194:197], v[30:33]
	v_mfma_f32_16x16x32_bf16 v[22:25], v[170:173], v[202:205], v[22:25]
	v_mfma_f32_16x16x32_bf16 v[14:17], v[178:181], v[202:205], v[14:17]
	v_mfma_f32_16x16x32_bf16 v[6:9], v[170:173], v[210:213], v[6:9]
	s_barrier
	v_mfma_f32_16x16x32_bf16 v[2:5], v[178:181], v[210:213], v[2:5]
	s_setprio 0
	s_add_i32 s50, s50, 2
	s_add_u32 s20, s20, 0x100
	s_addc_u32 s21, s21, 0
	s_cmp_gt_u32 s50, 13
	s_cbranch_scc0 .LBB0_968
	s_add_u32 s20, s48, 0xffffff00
	s_addc_u32 s21, s49, -1
	s_andn2_b64 vcc, exec, s[2:3]
	s_cbranch_vccnz .LBB0_959
	v_mov_b32_e32 v2, 0
	s_mov_b32 s6, s12
	s_mov_b32 s4, s14
	s_mov_b64 s[8:9], s[18:19]
	s_mov_b32 s44, s47
	v_mov_b32_e32 v3, v2
	v_mov_b32_e32 v4, v2
	v_mov_b32_e32 v5, v2
	v_mov_b32_e32 v6, v2
	v_mov_b32_e32 v7, v2
	v_mov_b32_e32 v8, v2
	v_mov_b32_e32 v9, v2
	v_mov_b32_e32 v14, v2
	v_mov_b32_e32 v15, v2
	v_mov_b32_e32 v16, v2
	v_mov_b32_e32 v17, v2
	v_mov_b32_e32 v22, v2
	v_mov_b32_e32 v23, v2
	v_mov_b32_e32 v24, v2
	v_mov_b32_e32 v25, v2
	v_mov_b32_e32 v30, v2
	v_mov_b32_e32 v31, v2
	v_mov_b32_e32 v32, v2
	v_mov_b32_e32 v33, v2
	v_mov_b32_e32 v38, v2
	v_mov_b32_e32 v39, v2
	v_mov_b32_e32 v40, v2
	v_mov_b32_e32 v41, v2
	v_mov_b32_e32 v46, v2
	v_mov_b32_e32 v47, v2
	v_mov_b32_e32 v48, v2
	v_mov_b32_e32 v49, v2
	v_mov_b32_e32 v54, v2
	v_mov_b32_e32 v55, v2
	v_mov_b32_e32 v56, v2
	v_mov_b32_e32 v57, v2
	v_mov_b32_e32 v10, v2
	v_mov_b32_e32 v11, v2
	v_mov_b32_e32 v12, v2
	v_mov_b32_e32 v13, v2
	v_mov_b32_e32 v18, v2
	v_mov_b32_e32 v19, v2
	v_mov_b32_e32 v20, v2
	v_mov_b32_e32 v21, v2
	v_mov_b32_e32 v26, v2
	v_mov_b32_e32 v27, v2
	v_mov_b32_e32 v28, v2
	v_mov_b32_e32 v29, v2
	v_mov_b32_e32 v34, v2
	v_mov_b32_e32 v35, v2
	v_mov_b32_e32 v36, v2
	v_mov_b32_e32 v37, v2
	v_mov_b32_e32 v42, v2
	v_mov_b32_e32 v43, v2
	v_mov_b32_e32 v44, v2
	v_mov_b32_e32 v45, v2
	v_mov_b32_e32 v50, v2
	v_mov_b32_e32 v51, v2
	v_mov_b32_e32 v52, v2
	v_mov_b32_e32 v53, v2
	v_mov_b32_e32 v58, v2
	v_mov_b32_e32 v59, v2
	v_mov_b32_e32 v60, v2
	v_mov_b32_e32 v61, v2
	v_mov_b32_e32 v62, v2
	v_mov_b32_e32 v63, v2
	v_mov_b32_e32 v64, v2
	v_mov_b32_e32 v65, v2
	v_mov_b32_e32 v66, v2
	v_mov_b32_e32 v67, v2
	v_mov_b32_e32 v68, v2
	v_mov_b32_e32 v69, v2
	v_mov_b32_e32 v70, v2
	v_mov_b32_e32 v71, v2
	v_mov_b32_e32 v72, v2
	v_mov_b32_e32 v73, v2
	v_mov_b32_e32 v78, v2
	v_mov_b32_e32 v79, v2
	v_mov_b32_e32 v80, v2
	v_mov_b32_e32 v81, v2
	v_mov_b32_e32 v86, v2
	v_mov_b32_e32 v87, v2
	v_mov_b32_e32 v88, v2
	v_mov_b32_e32 v89, v2
	v_mov_b32_e32 v94, v2
	v_mov_b32_e32 v95, v2
	v_mov_b32_e32 v96, v2
	v_mov_b32_e32 v97, v2
	v_mov_b32_e32 v102, v2
	v_mov_b32_e32 v103, v2
	v_mov_b32_e32 v104, v2
	v_mov_b32_e32 v105, v2
	v_mov_b32_e32 v110, v2
	v_mov_b32_e32 v111, v2
	v_mov_b32_e32 v112, v2
	v_mov_b32_e32 v113, v2
	v_mov_b32_e32 v118, v2
	v_mov_b32_e32 v119, v2
	v_mov_b32_e32 v120, v2
	v_mov_b32_e32 v121, v2
	v_mov_b32_e32 v74, v2
	v_mov_b32_e32 v75, v2
	v_mov_b32_e32 v76, v2
	v_mov_b32_e32 v77, v2
	v_mov_b32_e32 v82, v2
	v_mov_b32_e32 v83, v2
	v_mov_b32_e32 v84, v2
	v_mov_b32_e32 v85, v2
	v_mov_b32_e32 v90, v2
	v_mov_b32_e32 v91, v2
	v_mov_b32_e32 v92, v2
	v_mov_b32_e32 v93, v2
	v_mov_b32_e32 v98, v2
	v_mov_b32_e32 v99, v2
	v_mov_b32_e32 v100, v2
	v_mov_b32_e32 v101, v2
	v_mov_b32_e32 v106, v2
	v_mov_b32_e32 v107, v2
	v_mov_b32_e32 v108, v2
	v_mov_b32_e32 v109, v2
	v_mov_b32_e32 v114, v2
	v_mov_b32_e32 v115, v2
	v_mov_b32_e32 v116, v2
	v_mov_b32_e32 v117, v2
	v_mov_b32_e32 v122, v2
	v_mov_b32_e32 v123, v2
	v_mov_b32_e32 v124, v2
	v_mov_b32_e32 v125, v2
	v_mov_b32_e32 v126, v2
	v_mov_b32_e32 v127, v2
	v_mov_b32_e32 v128, v2
	v_mov_b32_e32 v129, v2
	s_andn2_b64 vcc, exec, s[0:1]
	s_cbranch_vccnz .LBB0_960
